# scan chunk loop rewritten: recurrence waves run continuously, helper waves do y reduction + split operand fill, one barrier per 8 steps
# baseline (speedup 1.0000x reference)
.LBB0_139:
	s_or_b64 exec, exec, s[12:13]
	s_lshl_b32 s0, s14, 2
	s_and_b32 s0, s0, 0x80
	v_lshl_or_b32 v2, v90, 2, s0
	s_lshl_b32 s0, s24, 2
	v_readlane_b32 s10, v254, 18
	s_and_b32 s0, s0, 32
	v_lshlrev_b64 v[0:1], 1, v[0:1]
	v_readlane_b32 s11, v254, 19
	v_lshl_add_u64 v[60:61], v[54:55], 0, v[0:1]
	v_lshl_add_u64 v[62:63], v[56:57], 0, v[0:1]
	v_lshl_add_u64 v[0:1], s[10:11], 0, v[0:1]
	s_lshl_b32 s26, s0, 1
	v_lshl_add_u64 v[0:1], v[0:1], 0, s[26:27]
	v_or_b32_e32 v98, 0xb00, v2
	v_or_b32_e32 v99, 0x6b00, v2
	v_mov_b32_e32 v2, v149
	v_mov_b32_e32 v3, v149
	v_lshl_add_u64 v[66:67], v[0:1], 0, v[148:149]
	v_mov_b32_e32 v0, v149
	v_mov_b32_e32 v1, v149
	v_mov_b64_e32 v[6:7], v[2:3]
	v_or_b32_e32 v59, s0, v90
	v_lshl_add_u64 v[64:65], s[38:39], 0, v[52:53]
	v_add_u32_e32 v145, 0xffffc000, v97
	s_mov_b32 s25, 0
	s_mov_b64 s[40:41], 0
	v_mov_b64_e32 v[4:5], v[0:1]
	s_waitcnt lgkmcnt(0)
	s_barrier
	s_branch .LBB0_141
.LBB0_141:
	s_and_b32 s45, s25, 1
	s_xor_b32 s44, s45, 1
	s_lshl_b32 s26, s25, 5
	s_mul_i32 s44, s44, 0xc000
	s_mul_i32 s42, s45, 0xc000
	v_add_u32_e32 v68, s26, v91
	s_cmp_lg_u64 s[8:9], 0
	s_cbranch_scc1 .Lsc_helper
	v_add_u32_e32 v69, s42, v92
	v_lshl_add_u32 v100, v59, 2, s42
	v_bfe_u32 v119, v171, 4, 2
	v_lshl_add_u32 v118, v119, 2, v100
	v_lshl_add_u32 v119, v119, 6, v94
	v_add_u32_e32 v119, 0x18000, v119
	s_setprio 3
	ds_read_b128 v[12:15], v69 offset:256
	ds_read_b128 v[20:23], v69 offset:768
	ds_read_b64 v[28:29], v118 offset:1280
	ds_read_b128 v[8:11], v69 offset:0
	ds_read_b128 v[16:19], v69 offset:512
	ds_read_b128 v[24:27], v69 offset:1024
	s_waitcnt lgkmcnt(0)
	v_pk_mul_f32 v[110:111], v[2:3], v[14:15]
	v_pk_mul_f32 v[112:113], v[6:7], v[14:15]
	v_pk_fma_f32 v[110:111], v[0:1], v[12:13], v[110:111]
	v_pk_fma_f32 v[112:113], v[4:5], v[12:13], v[112:113]
	ds_read_b128 v[34:37], v69 offset:1792
	ds_read_b128 v[78:81], v69 offset:2304
	ds_read_b64 v[108:109], v118 offset:2816
	ds_read_b128 v[30:33], v69 offset:1536
	ds_read_b128 v[74:77], v69 offset:2048
	ds_read_b128 v[104:107], v69 offset:2560
	v_add_f32_e32 v70, v110, v111
	v_add_f32_e32 v72, v112, v113
	v_pk_mul_f32 v[38:39], v[20:21], v[28:29] op_sel_hi:[1,0]
	v_add_f32_dpp v70, v70, v70 row_ror:8 row_mask:0xf bank_mask:0xf bound_ctrl:1
	v_add_f32_dpp v72, v72, v72 row_ror:8 row_mask:0xf bank_mask:0xf bound_ctrl:1
	v_pk_mul_f32 v[82:83], v[22:23], v[28:29] op_sel_hi:[1,0]
	v_add_f32_dpp v70, v70, v70 row_ror:4 row_mask:0xf bank_mask:0xf bound_ctrl:1
	v_add_f32_dpp v72, v72, v72 row_ror:4 row_mask:0xf bank_mask:0xf bound_ctrl:1
	v_pk_mul_f32 v[116:117], v[20:21], v[28:29] op_sel:[0,1] op_sel_hi:[1,1]
	v_add_f32_dpp v70, v70, v70 row_ror:2 row_mask:0xf bank_mask:0xf bound_ctrl:1
	v_add_f32_dpp v72, v72, v72 row_ror:2 row_mask:0xf bank_mask:0xf bound_ctrl:1
	v_pk_mul_f32 v[114:115], v[22:23], v[28:29] op_sel:[0,1] op_sel_hi:[1,1]
	v_add_f32_dpp v70, v70, v70 row_ror:1 row_mask:0xf bank_mask:0xf bound_ctrl:1
	v_add_f32_dpp v72, v72, v72 row_ror:1 row_mask:0xf bank_mask:0xf bound_ctrl:1
	v_pk_fma_f32 v[38:39], v[0:1], v[8:9], v[38:39]
	v_pk_fma_f32 v[82:83], v[2:3], v[10:11], v[82:83]
	v_pk_fma_f32 v[116:117], v[4:5], v[8:9], v[116:117]
	v_pk_fma_f32 v[114:115], v[6:7], v[10:11], v[114:115]
	v_pk_fma_f32 v[0:1], v[16:17], v[70:71], v[38:39] op_sel_hi:[1,0,1]
	v_pk_fma_f32 v[2:3], v[18:19], v[70:71], v[82:83] op_sel_hi:[1,0,1]
	v_pk_fma_f32 v[4:5], v[16:17], v[72:73], v[116:117] op_sel_hi:[1,0,1]
	v_pk_fma_f32 v[6:7], v[18:19], v[72:73], v[114:115] op_sel_hi:[1,0,1]
	v_pk_mul_f32 v[110:111], v[2:3], v[26:27]
	v_pk_mul_f32 v[112:113], v[6:7], v[26:27]
	v_pk_fma_f32 v[110:111], v[0:1], v[24:25], v[110:111]
	v_pk_fma_f32 v[112:113], v[4:5], v[24:25], v[112:113]
	v_add_f32_e32 v110, v110, v111
	v_add_f32_e32 v112, v112, v113
	ds_write_b32 v119, v110 offset:0
	ds_write_b32 v119, v112 offset:64
	s_waitcnt lgkmcnt(2)
	v_pk_mul_f32 v[110:111], v[2:3], v[36:37]
	v_pk_mul_f32 v[112:113], v[6:7], v[36:37]
	v_pk_fma_f32 v[110:111], v[0:1], v[34:35], v[110:111]
	v_pk_fma_f32 v[112:113], v[4:5], v[34:35], v[112:113]
	ds_read_b128 v[12:15], v69 offset:3328
	ds_read_b128 v[20:23], v69 offset:3840
	ds_read_b64 v[28:29], v118 offset:4352
	ds_read_b128 v[8:11], v69 offset:3072
	ds_read_b128 v[16:19], v69 offset:3584
	ds_read_b128 v[24:27], v69 offset:4096
	v_add_f32_e32 v70, v110, v111
	v_add_f32_e32 v72, v112, v113
	v_pk_mul_f32 v[38:39], v[78:79], v[108:109] op_sel_hi:[1,0]
	v_add_f32_dpp v70, v70, v70 row_ror:8 row_mask:0xf bank_mask:0xf bound_ctrl:1
	v_add_f32_dpp v72, v72, v72 row_ror:8 row_mask:0xf bank_mask:0xf bound_ctrl:1
	v_pk_mul_f32 v[82:83], v[80:81], v[108:109] op_sel_hi:[1,0]
	v_add_f32_dpp v70, v70, v70 row_ror:4 row_mask:0xf bank_mask:0xf bound_ctrl:1
	v_add_f32_dpp v72, v72, v72 row_ror:4 row_mask:0xf bank_mask:0xf bound_ctrl:1
	v_pk_mul_f32 v[116:117], v[78:79], v[108:109] op_sel:[0,1] op_sel_hi:[1,1]
	v_add_f32_dpp v70, v70, v70 row_ror:2 row_mask:0xf bank_mask:0xf bound_ctrl:1
	v_add_f32_dpp v72, v72, v72 row_ror:2 row_mask:0xf bank_mask:0xf bound_ctrl:1
	v_pk_mul_f32 v[114:115], v[80:81], v[108:109] op_sel:[0,1] op_sel_hi:[1,1]
	v_add_f32_dpp v70, v70, v70 row_ror:1 row_mask:0xf bank_mask:0xf bound_ctrl:1
	v_add_f32_dpp v72, v72, v72 row_ror:1 row_mask:0xf bank_mask:0xf bound_ctrl:1
	v_pk_fma_f32 v[38:39], v[0:1], v[30:31], v[38:39]
	v_pk_fma_f32 v[82:83], v[2:3], v[32:33], v[82:83]
	v_pk_fma_f32 v[116:117], v[4:5], v[30:31], v[116:117]
	v_pk_fma_f32 v[114:115], v[6:7], v[32:33], v[114:115]
	v_pk_fma_f32 v[0:1], v[74:75], v[70:71], v[38:39] op_sel_hi:[1,0,1]
	v_pk_fma_f32 v[2:3], v[76:77], v[70:71], v[82:83] op_sel_hi:[1,0,1]
	v_pk_fma_f32 v[4:5], v[74:75], v[72:73], v[116:117] op_sel_hi:[1,0,1]
	v_pk_fma_f32 v[6:7], v[76:77], v[72:73], v[114:115] op_sel_hi:[1,0,1]
	v_pk_mul_f32 v[110:111], v[2:3], v[106:107]
	v_pk_mul_f32 v[112:113], v[6:7], v[106:107]
	v_pk_fma_f32 v[110:111], v[0:1], v[104:105], v[110:111]
	v_pk_fma_f32 v[112:113], v[4:5], v[104:105], v[112:113]
	v_add_f32_e32 v110, v110, v111
	v_add_f32_e32 v112, v112, v113
	ds_write_b32 v119, v110 offset:2048
	ds_write_b32 v119, v112 offset:2112
	s_waitcnt lgkmcnt(2)
	v_pk_mul_f32 v[110:111], v[2:3], v[14:15]
	v_pk_mul_f32 v[112:113], v[6:7], v[14:15]
	v_pk_fma_f32 v[110:111], v[0:1], v[12:13], v[110:111]
	v_pk_fma_f32 v[112:113], v[4:5], v[12:13], v[112:113]
	ds_read_b128 v[34:37], v69 offset:4864
	ds_read_b128 v[78:81], v69 offset:5376
	ds_read_b64 v[108:109], v118 offset:5888
	ds_read_b128 v[30:33], v69 offset:4608
	ds_read_b128 v[74:77], v69 offset:5120
	ds_read_b128 v[104:107], v69 offset:5632
	v_add_f32_e32 v70, v110, v111
	v_add_f32_e32 v72, v112, v113
	v_pk_mul_f32 v[38:39], v[20:21], v[28:29] op_sel_hi:[1,0]
	v_add_f32_dpp v70, v70, v70 row_ror:8 row_mask:0xf bank_mask:0xf bound_ctrl:1
	v_add_f32_dpp v72, v72, v72 row_ror:8 row_mask:0xf bank_mask:0xf bound_ctrl:1
	v_pk_mul_f32 v[82:83], v[22:23], v[28:29] op_sel_hi:[1,0]
	v_add_f32_dpp v70, v70, v70 row_ror:4 row_mask:0xf bank_mask:0xf bound_ctrl:1
	v_add_f32_dpp v72, v72, v72 row_ror:4 row_mask:0xf bank_mask:0xf bound_ctrl:1
	v_pk_mul_f32 v[116:117], v[20:21], v[28:29] op_sel:[0,1] op_sel_hi:[1,1]
	v_add_f32_dpp v70, v70, v70 row_ror:2 row_mask:0xf bank_mask:0xf bound_ctrl:1
	v_add_f32_dpp v72, v72, v72 row_ror:2 row_mask:0xf bank_mask:0xf bound_ctrl:1
	v_pk_mul_f32 v[114:115], v[22:23], v[28:29] op_sel:[0,1] op_sel_hi:[1,1]
	v_add_f32_dpp v70, v70, v70 row_ror:1 row_mask:0xf bank_mask:0xf bound_ctrl:1
	v_add_f32_dpp v72, v72, v72 row_ror:1 row_mask:0xf bank_mask:0xf bound_ctrl:1
	v_pk_fma_f32 v[38:39], v[0:1], v[8:9], v[38:39]
	v_pk_fma_f32 v[82:83], v[2:3], v[10:11], v[82:83]
	v_pk_fma_f32 v[116:117], v[4:5], v[8:9], v[116:117]
	v_pk_fma_f32 v[114:115], v[6:7], v[10:11], v[114:115]
	v_pk_fma_f32 v[0:1], v[16:17], v[70:71], v[38:39] op_sel_hi:[1,0,1]
	v_pk_fma_f32 v[2:3], v[18:19], v[70:71], v[82:83] op_sel_hi:[1,0,1]
	v_pk_fma_f32 v[4:5], v[16:17], v[72:73], v[116:117] op_sel_hi:[1,0,1]
	v_pk_fma_f32 v[6:7], v[18:19], v[72:73], v[114:115] op_sel_hi:[1,0,1]
	v_pk_mul_f32 v[110:111], v[2:3], v[26:27]
	v_pk_mul_f32 v[112:113], v[6:7], v[26:27]
	v_pk_fma_f32 v[110:111], v[0:1], v[24:25], v[110:111]
	v_pk_fma_f32 v[112:113], v[4:5], v[24:25], v[112:113]
	v_add_f32_e32 v110, v110, v111
	v_add_f32_e32 v112, v112, v113
	ds_write_b32 v119, v110 offset:4096
	ds_write_b32 v119, v112 offset:4160
	s_waitcnt lgkmcnt(2)
	v_pk_mul_f32 v[110:111], v[2:3], v[36:37]
	v_pk_mul_f32 v[112:113], v[6:7], v[36:37]
	v_pk_fma_f32 v[110:111], v[0:1], v[34:35], v[110:111]
	v_pk_fma_f32 v[112:113], v[4:5], v[34:35], v[112:113]
	ds_read_b128 v[12:15], v69 offset:6400
	ds_read_b128 v[20:23], v69 offset:6912
	ds_read_b64 v[28:29], v118 offset:7424
	ds_read_b128 v[8:11], v69 offset:6144
	ds_read_b128 v[16:19], v69 offset:6656
	ds_read_b128 v[24:27], v69 offset:7168
	v_add_f32_e32 v70, v110, v111
	v_add_f32_e32 v72, v112, v113
	v_pk_mul_f32 v[38:39], v[78:79], v[108:109] op_sel_hi:[1,0]
	v_add_f32_dpp v70, v70, v70 row_ror:8 row_mask:0xf bank_mask:0xf bound_ctrl:1
	v_add_f32_dpp v72, v72, v72 row_ror:8 row_mask:0xf bank_mask:0xf bound_ctrl:1
	v_pk_mul_f32 v[82:83], v[80:81], v[108:109] op_sel_hi:[1,0]
	v_add_f32_dpp v70, v70, v70 row_ror:4 row_mask:0xf bank_mask:0xf bound_ctrl:1
	v_add_f32_dpp v72, v72, v72 row_ror:4 row_mask:0xf bank_mask:0xf bound_ctrl:1
	v_pk_mul_f32 v[116:117], v[78:79], v[108:109] op_sel:[0,1] op_sel_hi:[1,1]
	v_add_f32_dpp v70, v70, v70 row_ror:2 row_mask:0xf bank_mask:0xf bound_ctrl:1
	v_add_f32_dpp v72, v72, v72 row_ror:2 row_mask:0xf bank_mask:0xf bound_ctrl:1
	v_pk_mul_f32 v[114:115], v[80:81], v[108:109] op_sel:[0,1] op_sel_hi:[1,1]
	v_add_f32_dpp v70, v70, v70 row_ror:1 row_mask:0xf bank_mask:0xf bound_ctrl:1
	v_add_f32_dpp v72, v72, v72 row_ror:1 row_mask:0xf bank_mask:0xf bound_ctrl:1
	v_pk_fma_f32 v[38:39], v[0:1], v[30:31], v[38:39]
	v_pk_fma_f32 v[82:83], v[2:3], v[32:33], v[82:83]
	v_pk_fma_f32 v[116:117], v[4:5], v[30:31], v[116:117]
	v_pk_fma_f32 v[114:115], v[6:7], v[32:33], v[114:115]
	v_pk_fma_f32 v[0:1], v[74:75], v[70:71], v[38:39] op_sel_hi:[1,0,1]
	v_pk_fma_f32 v[2:3], v[76:77], v[70:71], v[82:83] op_sel_hi:[1,0,1]
	v_pk_fma_f32 v[4:5], v[74:75], v[72:73], v[116:117] op_sel_hi:[1,0,1]
	v_pk_fma_f32 v[6:7], v[76:77], v[72:73], v[114:115] op_sel_hi:[1,0,1]
	v_pk_mul_f32 v[110:111], v[2:3], v[106:107]
	v_pk_mul_f32 v[112:113], v[6:7], v[106:107]
	v_pk_fma_f32 v[110:111], v[0:1], v[104:105], v[110:111]
	v_pk_fma_f32 v[112:113], v[4:5], v[104:105], v[112:113]
	v_add_f32_e32 v110, v110, v111
	v_add_f32_e32 v112, v112, v113
	ds_write_b32 v119, v110 offset:6144
	ds_write_b32 v119, v112 offset:6208
	s_waitcnt lgkmcnt(2)
	v_pk_mul_f32 v[110:111], v[2:3], v[14:15]
	v_pk_mul_f32 v[112:113], v[6:7], v[14:15]
	v_pk_fma_f32 v[110:111], v[0:1], v[12:13], v[110:111]
	v_pk_fma_f32 v[112:113], v[4:5], v[12:13], v[112:113]
	ds_read_b128 v[34:37], v69 offset:7936
	ds_read_b128 v[78:81], v69 offset:8448
	ds_read_b64 v[108:109], v118 offset:8960
	ds_read_b128 v[30:33], v69 offset:7680
	ds_read_b128 v[74:77], v69 offset:8192
	ds_read_b128 v[104:107], v69 offset:8704
	v_add_f32_e32 v70, v110, v111
	v_add_f32_e32 v72, v112, v113
	v_pk_mul_f32 v[38:39], v[20:21], v[28:29] op_sel_hi:[1,0]
	v_add_f32_dpp v70, v70, v70 row_ror:8 row_mask:0xf bank_mask:0xf bound_ctrl:1
	v_add_f32_dpp v72, v72, v72 row_ror:8 row_mask:0xf bank_mask:0xf bound_ctrl:1
	v_pk_mul_f32 v[82:83], v[22:23], v[28:29] op_sel_hi:[1,0]
	v_add_f32_dpp v70, v70, v70 row_ror:4 row_mask:0xf bank_mask:0xf bound_ctrl:1
	v_add_f32_dpp v72, v72, v72 row_ror:4 row_mask:0xf bank_mask:0xf bound_ctrl:1
	v_pk_mul_f32 v[116:117], v[20:21], v[28:29] op_sel:[0,1] op_sel_hi:[1,1]
	v_add_f32_dpp v70, v70, v70 row_ror:2 row_mask:0xf bank_mask:0xf bound_ctrl:1
	v_add_f32_dpp v72, v72, v72 row_ror:2 row_mask:0xf bank_mask:0xf bound_ctrl:1
	v_pk_mul_f32 v[114:115], v[22:23], v[28:29] op_sel:[0,1] op_sel_hi:[1,1]
	v_add_f32_dpp v70, v70, v70 row_ror:1 row_mask:0xf bank_mask:0xf bound_ctrl:1
	v_add_f32_dpp v72, v72, v72 row_ror:1 row_mask:0xf bank_mask:0xf bound_ctrl:1
	v_pk_fma_f32 v[38:39], v[0:1], v[8:9], v[38:39]
	v_pk_fma_f32 v[82:83], v[2:3], v[10:11], v[82:83]
	v_pk_fma_f32 v[116:117], v[4:5], v[8:9], v[116:117]
	v_pk_fma_f32 v[114:115], v[6:7], v[10:11], v[114:115]
	v_pk_fma_f32 v[0:1], v[16:17], v[70:71], v[38:39] op_sel_hi:[1,0,1]
	v_pk_fma_f32 v[2:3], v[18:19], v[70:71], v[82:83] op_sel_hi:[1,0,1]
	v_pk_fma_f32 v[4:5], v[16:17], v[72:73], v[116:117] op_sel_hi:[1,0,1]
	v_pk_fma_f32 v[6:7], v[18:19], v[72:73], v[114:115] op_sel_hi:[1,0,1]
	v_pk_mul_f32 v[110:111], v[2:3], v[26:27]
	v_pk_mul_f32 v[112:113], v[6:7], v[26:27]
	v_pk_fma_f32 v[110:111], v[0:1], v[24:25], v[110:111]
	v_pk_fma_f32 v[112:113], v[4:5], v[24:25], v[112:113]
	v_add_f32_e32 v110, v110, v111
	v_add_f32_e32 v112, v112, v113
	ds_write_b32 v119, v110 offset:8192
	ds_write_b32 v119, v112 offset:8256
	s_waitcnt lgkmcnt(2)
	v_pk_mul_f32 v[110:111], v[2:3], v[36:37]
	v_pk_mul_f32 v[112:113], v[6:7], v[36:37]
	v_pk_fma_f32 v[110:111], v[0:1], v[34:35], v[110:111]
	v_pk_fma_f32 v[112:113], v[4:5], v[34:35], v[112:113]
	ds_read_b128 v[12:15], v69 offset:9472
	ds_read_b128 v[20:23], v69 offset:9984
	ds_read_b64 v[28:29], v118 offset:10496
	ds_read_b128 v[8:11], v69 offset:9216
	ds_read_b128 v[16:19], v69 offset:9728
	ds_read_b128 v[24:27], v69 offset:10240
	v_add_f32_e32 v70, v110, v111
	v_add_f32_e32 v72, v112, v113
	v_pk_mul_f32 v[38:39], v[78:79], v[108:109] op_sel_hi:[1,0]
	v_add_f32_dpp v70, v70, v70 row_ror:8 row_mask:0xf bank_mask:0xf bound_ctrl:1
	v_add_f32_dpp v72, v72, v72 row_ror:8 row_mask:0xf bank_mask:0xf bound_ctrl:1
	v_pk_mul_f32 v[82:83], v[80:81], v[108:109] op_sel_hi:[1,0]
	v_add_f32_dpp v70, v70, v70 row_ror:4 row_mask:0xf bank_mask:0xf bound_ctrl:1
	v_add_f32_dpp v72, v72, v72 row_ror:4 row_mask:0xf bank_mask:0xf bound_ctrl:1
	v_pk_mul_f32 v[116:117], v[78:79], v[108:109] op_sel:[0,1] op_sel_hi:[1,1]
	v_add_f32_dpp v70, v70, v70 row_ror:2 row_mask:0xf bank_mask:0xf bound_ctrl:1
	v_add_f32_dpp v72, v72, v72 row_ror:2 row_mask:0xf bank_mask:0xf bound_ctrl:1
	v_pk_mul_f32 v[114:115], v[80:81], v[108:109] op_sel:[0,1] op_sel_hi:[1,1]
	v_add_f32_dpp v70, v70, v70 row_ror:1 row_mask:0xf bank_mask:0xf bound_ctrl:1
	v_add_f32_dpp v72, v72, v72 row_ror:1 row_mask:0xf bank_mask:0xf bound_ctrl:1
	v_pk_fma_f32 v[38:39], v[0:1], v[30:31], v[38:39]
	v_pk_fma_f32 v[82:83], v[2:3], v[32:33], v[82:83]
	v_pk_fma_f32 v[116:117], v[4:5], v[30:31], v[116:117]
	v_pk_fma_f32 v[114:115], v[6:7], v[32:33], v[114:115]
	v_pk_fma_f32 v[0:1], v[74:75], v[70:71], v[38:39] op_sel_hi:[1,0,1]
	v_pk_fma_f32 v[2:3], v[76:77], v[70:71], v[82:83] op_sel_hi:[1,0,1]
	v_pk_fma_f32 v[4:5], v[74:75], v[72:73], v[116:117] op_sel_hi:[1,0,1]
	v_pk_fma_f32 v[6:7], v[76:77], v[72:73], v[114:115] op_sel_hi:[1,0,1]
	v_pk_mul_f32 v[110:111], v[2:3], v[106:107]
	v_pk_mul_f32 v[112:113], v[6:7], v[106:107]
	v_pk_fma_f32 v[110:111], v[0:1], v[104:105], v[110:111]
	v_pk_fma_f32 v[112:113], v[4:5], v[104:105], v[112:113]
	v_add_f32_e32 v110, v110, v111
	v_add_f32_e32 v112, v112, v113
	ds_write_b32 v119, v110 offset:10240
	ds_write_b32 v119, v112 offset:10304
	s_waitcnt lgkmcnt(2)
	v_pk_mul_f32 v[110:111], v[2:3], v[14:15]
	v_pk_mul_f32 v[112:113], v[6:7], v[14:15]
	v_pk_fma_f32 v[110:111], v[0:1], v[12:13], v[110:111]
	v_pk_fma_f32 v[112:113], v[4:5], v[12:13], v[112:113]
	ds_read_b128 v[34:37], v69 offset:11008
	ds_read_b128 v[78:81], v69 offset:11520
	ds_read_b64 v[108:109], v118 offset:12032
	ds_read_b128 v[30:33], v69 offset:10752
	ds_read_b128 v[74:77], v69 offset:11264
	ds_read_b128 v[104:107], v69 offset:11776
	v_add_f32_e32 v70, v110, v111
	v_add_f32_e32 v72, v112, v113
	v_pk_mul_f32 v[38:39], v[20:21], v[28:29] op_sel_hi:[1,0]
	v_add_f32_dpp v70, v70, v70 row_ror:8 row_mask:0xf bank_mask:0xf bound_ctrl:1
	v_add_f32_dpp v72, v72, v72 row_ror:8 row_mask:0xf bank_mask:0xf bound_ctrl:1
	v_pk_mul_f32 v[82:83], v[22:23], v[28:29] op_sel_hi:[1,0]
	v_add_f32_dpp v70, v70, v70 row_ror:4 row_mask:0xf bank_mask:0xf bound_ctrl:1
	v_add_f32_dpp v72, v72, v72 row_ror:4 row_mask:0xf bank_mask:0xf bound_ctrl:1
	v_pk_mul_f32 v[116:117], v[20:21], v[28:29] op_sel:[0,1] op_sel_hi:[1,1]
	v_add_f32_dpp v70, v70, v70 row_ror:2 row_mask:0xf bank_mask:0xf bound_ctrl:1
	v_add_f32_dpp v72, v72, v72 row_ror:2 row_mask:0xf bank_mask:0xf bound_ctrl:1
	v_pk_mul_f32 v[114:115], v[22:23], v[28:29] op_sel:[0,1] op_sel_hi:[1,1]
	v_add_f32_dpp v70, v70, v70 row_ror:1 row_mask:0xf bank_mask:0xf bound_ctrl:1
	v_add_f32_dpp v72, v72, v72 row_ror:1 row_mask:0xf bank_mask:0xf bound_ctrl:1
	v_pk_fma_f32 v[38:39], v[0:1], v[8:9], v[38:39]
	v_pk_fma_f32 v[82:83], v[2:3], v[10:11], v[82:83]
	v_pk_fma_f32 v[116:117], v[4:5], v[8:9], v[116:117]
	v_pk_fma_f32 v[114:115], v[6:7], v[10:11], v[114:115]
	v_pk_fma_f32 v[0:1], v[16:17], v[70:71], v[38:39] op_sel_hi:[1,0,1]
	v_pk_fma_f32 v[2:3], v[18:19], v[70:71], v[82:83] op_sel_hi:[1,0,1]
	v_pk_fma_f32 v[4:5], v[16:17], v[72:73], v[116:117] op_sel_hi:[1,0,1]
	v_pk_fma_f32 v[6:7], v[18:19], v[72:73], v[114:115] op_sel_hi:[1,0,1]
	v_pk_mul_f32 v[110:111], v[2:3], v[26:27]
	v_pk_mul_f32 v[112:113], v[6:7], v[26:27]
	v_pk_fma_f32 v[110:111], v[0:1], v[24:25], v[110:111]
	v_pk_fma_f32 v[112:113], v[4:5], v[24:25], v[112:113]
	v_add_f32_e32 v110, v110, v111
	v_add_f32_e32 v112, v112, v113
	ds_write_b32 v119, v110 offset:12288
	ds_write_b32 v119, v112 offset:12352
	s_waitcnt lgkmcnt(2)
	v_pk_mul_f32 v[110:111], v[2:3], v[36:37]
	v_pk_mul_f32 v[112:113], v[6:7], v[36:37]
	v_pk_fma_f32 v[110:111], v[0:1], v[34:35], v[110:111]
	v_pk_fma_f32 v[112:113], v[4:5], v[34:35], v[112:113]
	ds_read_b128 v[12:15], v69 offset:12544
	ds_read_b128 v[20:23], v69 offset:13056
	ds_read_b64 v[28:29], v118 offset:13568
	ds_read_b128 v[8:11], v69 offset:12288
	ds_read_b128 v[16:19], v69 offset:12800
	ds_read_b128 v[24:27], v69 offset:13312
	v_add_f32_e32 v70, v110, v111
	v_add_f32_e32 v72, v112, v113
	v_pk_mul_f32 v[38:39], v[78:79], v[108:109] op_sel_hi:[1,0]
	v_add_f32_dpp v70, v70, v70 row_ror:8 row_mask:0xf bank_mask:0xf bound_ctrl:1
	v_add_f32_dpp v72, v72, v72 row_ror:8 row_mask:0xf bank_mask:0xf bound_ctrl:1
	v_pk_mul_f32 v[82:83], v[80:81], v[108:109] op_sel_hi:[1,0]
	v_add_f32_dpp v70, v70, v70 row_ror:4 row_mask:0xf bank_mask:0xf bound_ctrl:1
	v_add_f32_dpp v72, v72, v72 row_ror:4 row_mask:0xf bank_mask:0xf bound_ctrl:1
	v_pk_mul_f32 v[116:117], v[78:79], v[108:109] op_sel:[0,1] op_sel_hi:[1,1]
	v_add_f32_dpp v70, v70, v70 row_ror:2 row_mask:0xf bank_mask:0xf bound_ctrl:1
	v_add_f32_dpp v72, v72, v72 row_ror:2 row_mask:0xf bank_mask:0xf bound_ctrl:1
	v_pk_mul_f32 v[114:115], v[80:81], v[108:109] op_sel:[0,1] op_sel_hi:[1,1]
	v_add_f32_dpp v70, v70, v70 row_ror:1 row_mask:0xf bank_mask:0xf bound_ctrl:1
	v_add_f32_dpp v72, v72, v72 row_ror:1 row_mask:0xf bank_mask:0xf bound_ctrl:1
	v_pk_fma_f32 v[38:39], v[0:1], v[30:31], v[38:39]
	v_pk_fma_f32 v[82:83], v[2:3], v[32:33], v[82:83]
	v_pk_fma_f32 v[116:117], v[4:5], v[30:31], v[116:117]
	v_pk_fma_f32 v[114:115], v[6:7], v[32:33], v[114:115]
	v_pk_fma_f32 v[0:1], v[74:75], v[70:71], v[38:39] op_sel_hi:[1,0,1]
	v_pk_fma_f32 v[2:3], v[76:77], v[70:71], v[82:83] op_sel_hi:[1,0,1]
	v_pk_fma_f32 v[4:5], v[74:75], v[72:73], v[116:117] op_sel_hi:[1,0,1]
	v_pk_fma_f32 v[6:7], v[76:77], v[72:73], v[114:115] op_sel_hi:[1,0,1]
	v_pk_mul_f32 v[110:111], v[2:3], v[106:107]
	v_pk_mul_f32 v[112:113], v[6:7], v[106:107]
	v_pk_fma_f32 v[110:111], v[0:1], v[104:105], v[110:111]
	v_pk_fma_f32 v[112:113], v[4:5], v[104:105], v[112:113]
	v_add_f32_e32 v110, v110, v111
	v_add_f32_e32 v112, v112, v113
	ds_write_b32 v119, v110 offset:14336
	ds_write_b32 v119, v112 offset:14400
	s_waitcnt lgkmcnt(0)
	s_barrier
	v_pk_mul_f32 v[110:111], v[2:3], v[14:15]
	v_pk_mul_f32 v[112:113], v[6:7], v[14:15]
	v_pk_fma_f32 v[110:111], v[0:1], v[12:13], v[110:111]
	v_pk_fma_f32 v[112:113], v[4:5], v[12:13], v[112:113]
	ds_read_b128 v[34:37], v69 offset:14080
	ds_read_b128 v[78:81], v69 offset:14592
	ds_read_b64 v[108:109], v118 offset:15104
	ds_read_b128 v[30:33], v69 offset:13824
	ds_read_b128 v[74:77], v69 offset:14336
	ds_read_b128 v[104:107], v69 offset:14848
	v_add_f32_e32 v70, v110, v111
	v_add_f32_e32 v72, v112, v113
	v_pk_mul_f32 v[38:39], v[20:21], v[28:29] op_sel_hi:[1,0]
	v_add_f32_dpp v70, v70, v70 row_ror:8 row_mask:0xf bank_mask:0xf bound_ctrl:1
	v_add_f32_dpp v72, v72, v72 row_ror:8 row_mask:0xf bank_mask:0xf bound_ctrl:1
	v_pk_mul_f32 v[82:83], v[22:23], v[28:29] op_sel_hi:[1,0]
	v_add_f32_dpp v70, v70, v70 row_ror:4 row_mask:0xf bank_mask:0xf bound_ctrl:1
	v_add_f32_dpp v72, v72, v72 row_ror:4 row_mask:0xf bank_mask:0xf bound_ctrl:1
	v_pk_mul_f32 v[116:117], v[20:21], v[28:29] op_sel:[0,1] op_sel_hi:[1,1]
	v_add_f32_dpp v70, v70, v70 row_ror:2 row_mask:0xf bank_mask:0xf bound_ctrl:1
	v_add_f32_dpp v72, v72, v72 row_ror:2 row_mask:0xf bank_mask:0xf bound_ctrl:1
	v_pk_mul_f32 v[114:115], v[22:23], v[28:29] op_sel:[0,1] op_sel_hi:[1,1]
	v_add_f32_dpp v70, v70, v70 row_ror:1 row_mask:0xf bank_mask:0xf bound_ctrl:1
	v_add_f32_dpp v72, v72, v72 row_ror:1 row_mask:0xf bank_mask:0xf bound_ctrl:1
	v_pk_fma_f32 v[38:39], v[0:1], v[8:9], v[38:39]
	v_pk_fma_f32 v[82:83], v[2:3], v[10:11], v[82:83]
	v_pk_fma_f32 v[116:117], v[4:5], v[8:9], v[116:117]
	v_pk_fma_f32 v[114:115], v[6:7], v[10:11], v[114:115]
	v_pk_fma_f32 v[0:1], v[16:17], v[70:71], v[38:39] op_sel_hi:[1,0,1]
	v_pk_fma_f32 v[2:3], v[18:19], v[70:71], v[82:83] op_sel_hi:[1,0,1]
	v_pk_fma_f32 v[4:5], v[16:17], v[72:73], v[116:117] op_sel_hi:[1,0,1]
	v_pk_fma_f32 v[6:7], v[18:19], v[72:73], v[114:115] op_sel_hi:[1,0,1]
	v_pk_mul_f32 v[110:111], v[2:3], v[26:27]
	v_pk_mul_f32 v[112:113], v[6:7], v[26:27]
	v_pk_fma_f32 v[110:111], v[0:1], v[24:25], v[110:111]
	v_pk_fma_f32 v[112:113], v[4:5], v[24:25], v[112:113]
	v_add_f32_e32 v110, v110, v111
	v_add_f32_e32 v112, v112, v113
	ds_write_b32 v119, v110 offset:16384
	ds_write_b32 v119, v112 offset:16448
	s_waitcnt lgkmcnt(2)
	v_pk_mul_f32 v[110:111], v[2:3], v[36:37]
	v_pk_mul_f32 v[112:113], v[6:7], v[36:37]
	v_pk_fma_f32 v[110:111], v[0:1], v[34:35], v[110:111]
	v_pk_fma_f32 v[112:113], v[4:5], v[34:35], v[112:113]
	ds_read_b128 v[12:15], v69 offset:15616
	ds_read_b128 v[20:23], v69 offset:16128
	ds_read_b64 v[28:29], v118 offset:16640
	ds_read_b128 v[8:11], v69 offset:15360
	ds_read_b128 v[16:19], v69 offset:15872
	ds_read_b128 v[24:27], v69 offset:16384
	v_add_f32_e32 v70, v110, v111
	v_add_f32_e32 v72, v112, v113
	v_pk_mul_f32 v[38:39], v[78:79], v[108:109] op_sel_hi:[1,0]
	v_add_f32_dpp v70, v70, v70 row_ror:8 row_mask:0xf bank_mask:0xf bound_ctrl:1
	v_add_f32_dpp v72, v72, v72 row_ror:8 row_mask:0xf bank_mask:0xf bound_ctrl:1
	v_pk_mul_f32 v[82:83], v[80:81], v[108:109] op_sel_hi:[1,0]
	v_add_f32_dpp v70, v70, v70 row_ror:4 row_mask:0xf bank_mask:0xf bound_ctrl:1
	v_add_f32_dpp v72, v72, v72 row_ror:4 row_mask:0xf bank_mask:0xf bound_ctrl:1
	v_pk_mul_f32 v[116:117], v[78:79], v[108:109] op_sel:[0,1] op_sel_hi:[1,1]
	v_add_f32_dpp v70, v70, v70 row_ror:2 row_mask:0xf bank_mask:0xf bound_ctrl:1
	v_add_f32_dpp v72, v72, v72 row_ror:2 row_mask:0xf bank_mask:0xf bound_ctrl:1
	v_pk_mul_f32 v[114:115], v[80:81], v[108:109] op_sel:[0,1] op_sel_hi:[1,1]
	v_add_f32_dpp v70, v70, v70 row_ror:1 row_mask:0xf bank_mask:0xf bound_ctrl:1
	v_add_f32_dpp v72, v72, v72 row_ror:1 row_mask:0xf bank_mask:0xf bound_ctrl:1
	v_pk_fma_f32 v[38:39], v[0:1], v[30:31], v[38:39]
	v_pk_fma_f32 v[82:83], v[2:3], v[32:33], v[82:83]
	v_pk_fma_f32 v[116:117], v[4:5], v[30:31], v[116:117]
	v_pk_fma_f32 v[114:115], v[6:7], v[32:33], v[114:115]
	v_pk_fma_f32 v[0:1], v[74:75], v[70:71], v[38:39] op_sel_hi:[1,0,1]
	v_pk_fma_f32 v[2:3], v[76:77], v[70:71], v[82:83] op_sel_hi:[1,0,1]
	v_pk_fma_f32 v[4:5], v[74:75], v[72:73], v[116:117] op_sel_hi:[1,0,1]
	v_pk_fma_f32 v[6:7], v[76:77], v[72:73], v[114:115] op_sel_hi:[1,0,1]
	v_pk_mul_f32 v[110:111], v[2:3], v[106:107]
	v_pk_mul_f32 v[112:113], v[6:7], v[106:107]
	v_pk_fma_f32 v[110:111], v[0:1], v[104:105], v[110:111]
	v_pk_fma_f32 v[112:113], v[4:5], v[104:105], v[112:113]
	v_add_f32_e32 v110, v110, v111
	v_add_f32_e32 v112, v112, v113
	ds_write_b32 v119, v110 offset:18432
	ds_write_b32 v119, v112 offset:18496
	s_waitcnt lgkmcnt(2)
	v_pk_mul_f32 v[110:111], v[2:3], v[14:15]
	v_pk_mul_f32 v[112:113], v[6:7], v[14:15]
	v_pk_fma_f32 v[110:111], v[0:1], v[12:13], v[110:111]
	v_pk_fma_f32 v[112:113], v[4:5], v[12:13], v[112:113]
	ds_read_b128 v[34:37], v69 offset:17152
	ds_read_b128 v[78:81], v69 offset:17664
	ds_read_b64 v[108:109], v118 offset:18176
	ds_read_b128 v[30:33], v69 offset:16896
	ds_read_b128 v[74:77], v69 offset:17408
	ds_read_b128 v[104:107], v69 offset:17920
	v_add_f32_e32 v70, v110, v111
	v_add_f32_e32 v72, v112, v113
	v_pk_mul_f32 v[38:39], v[20:21], v[28:29] op_sel_hi:[1,0]
	v_add_f32_dpp v70, v70, v70 row_ror:8 row_mask:0xf bank_mask:0xf bound_ctrl:1
	v_add_f32_dpp v72, v72, v72 row_ror:8 row_mask:0xf bank_mask:0xf bound_ctrl:1
	v_pk_mul_f32 v[82:83], v[22:23], v[28:29] op_sel_hi:[1,0]
	v_add_f32_dpp v70, v70, v70 row_ror:4 row_mask:0xf bank_mask:0xf bound_ctrl:1
	v_add_f32_dpp v72, v72, v72 row_ror:4 row_mask:0xf bank_mask:0xf bound_ctrl:1
	v_pk_mul_f32 v[116:117], v[20:21], v[28:29] op_sel:[0,1] op_sel_hi:[1,1]
	v_add_f32_dpp v70, v70, v70 row_ror:2 row_mask:0xf bank_mask:0xf bound_ctrl:1
	v_add_f32_dpp v72, v72, v72 row_ror:2 row_mask:0xf bank_mask:0xf bound_ctrl:1
	v_pk_mul_f32 v[114:115], v[22:23], v[28:29] op_sel:[0,1] op_sel_hi:[1,1]
	v_add_f32_dpp v70, v70, v70 row_ror:1 row_mask:0xf bank_mask:0xf bound_ctrl:1
	v_add_f32_dpp v72, v72, v72 row_ror:1 row_mask:0xf bank_mask:0xf bound_ctrl:1
	v_pk_fma_f32 v[38:39], v[0:1], v[8:9], v[38:39]
	v_pk_fma_f32 v[82:83], v[2:3], v[10:11], v[82:83]
	v_pk_fma_f32 v[116:117], v[4:5], v[8:9], v[116:117]
	v_pk_fma_f32 v[114:115], v[6:7], v[10:11], v[114:115]
	v_pk_fma_f32 v[0:1], v[16:17], v[70:71], v[38:39] op_sel_hi:[1,0,1]
	v_pk_fma_f32 v[2:3], v[18:19], v[70:71], v[82:83] op_sel_hi:[1,0,1]
	v_pk_fma_f32 v[4:5], v[16:17], v[72:73], v[116:117] op_sel_hi:[1,0,1]
	v_pk_fma_f32 v[6:7], v[18:19], v[72:73], v[114:115] op_sel_hi:[1,0,1]
	v_pk_mul_f32 v[110:111], v[2:3], v[26:27]
	v_pk_mul_f32 v[112:113], v[6:7], v[26:27]
	v_pk_fma_f32 v[110:111], v[0:1], v[24:25], v[110:111]
	v_pk_fma_f32 v[112:113], v[4:5], v[24:25], v[112:113]
	v_add_f32_e32 v110, v110, v111
	v_add_f32_e32 v112, v112, v113
	ds_write_b32 v119, v110 offset:20480
	ds_write_b32 v119, v112 offset:20544
	s_waitcnt lgkmcnt(2)
	v_pk_mul_f32 v[110:111], v[2:3], v[36:37]
	v_pk_mul_f32 v[112:113], v[6:7], v[36:37]
	v_pk_fma_f32 v[110:111], v[0:1], v[34:35], v[110:111]
	v_pk_fma_f32 v[112:113], v[4:5], v[34:35], v[112:113]
	ds_read_b128 v[12:15], v69 offset:18688
	ds_read_b128 v[20:23], v69 offset:19200
	ds_read_b64 v[28:29], v118 offset:19712
	ds_read_b128 v[8:11], v69 offset:18432
	ds_read_b128 v[16:19], v69 offset:18944
	ds_read_b128 v[24:27], v69 offset:19456
	v_add_f32_e32 v70, v110, v111
	v_add_f32_e32 v72, v112, v113
	v_pk_mul_f32 v[38:39], v[78:79], v[108:109] op_sel_hi:[1,0]
	v_add_f32_dpp v70, v70, v70 row_ror:8 row_mask:0xf bank_mask:0xf bound_ctrl:1
	v_add_f32_dpp v72, v72, v72 row_ror:8 row_mask:0xf bank_mask:0xf bound_ctrl:1
	v_pk_mul_f32 v[82:83], v[80:81], v[108:109] op_sel_hi:[1,0]
	v_add_f32_dpp v70, v70, v70 row_ror:4 row_mask:0xf bank_mask:0xf bound_ctrl:1
	v_add_f32_dpp v72, v72, v72 row_ror:4 row_mask:0xf bank_mask:0xf bound_ctrl:1
	v_pk_mul_f32 v[116:117], v[78:79], v[108:109] op_sel:[0,1] op_sel_hi:[1,1]
	v_add_f32_dpp v70, v70, v70 row_ror:2 row_mask:0xf bank_mask:0xf bound_ctrl:1
	v_add_f32_dpp v72, v72, v72 row_ror:2 row_mask:0xf bank_mask:0xf bound_ctrl:1
	v_pk_mul_f32 v[114:115], v[80:81], v[108:109] op_sel:[0,1] op_sel_hi:[1,1]
	v_add_f32_dpp v70, v70, v70 row_ror:1 row_mask:0xf bank_mask:0xf bound_ctrl:1
	v_add_f32_dpp v72, v72, v72 row_ror:1 row_mask:0xf bank_mask:0xf bound_ctrl:1
	v_pk_fma_f32 v[38:39], v[0:1], v[30:31], v[38:39]
	v_pk_fma_f32 v[82:83], v[2:3], v[32:33], v[82:83]
	v_pk_fma_f32 v[116:117], v[4:5], v[30:31], v[116:117]
	v_pk_fma_f32 v[114:115], v[6:7], v[32:33], v[114:115]
	v_pk_fma_f32 v[0:1], v[74:75], v[70:71], v[38:39] op_sel_hi:[1,0,1]
	v_pk_fma_f32 v[2:3], v[76:77], v[70:71], v[82:83] op_sel_hi:[1,0,1]
	v_pk_fma_f32 v[4:5], v[74:75], v[72:73], v[116:117] op_sel_hi:[1,0,1]
	v_pk_fma_f32 v[6:7], v[76:77], v[72:73], v[114:115] op_sel_hi:[1,0,1]
	v_pk_mul_f32 v[110:111], v[2:3], v[106:107]
	v_pk_mul_f32 v[112:113], v[6:7], v[106:107]
	v_pk_fma_f32 v[110:111], v[0:1], v[104:105], v[110:111]
	v_pk_fma_f32 v[112:113], v[4:5], v[104:105], v[112:113]
	v_add_f32_e32 v110, v110, v111
	v_add_f32_e32 v112, v112, v113
	ds_write_b32 v119, v110 offset:22528
	ds_write_b32 v119, v112 offset:22592
	s_waitcnt lgkmcnt(2)
	v_pk_mul_f32 v[110:111], v[2:3], v[14:15]
	v_pk_mul_f32 v[112:113], v[6:7], v[14:15]
	v_pk_fma_f32 v[110:111], v[0:1], v[12:13], v[110:111]
	v_pk_fma_f32 v[112:113], v[4:5], v[12:13], v[112:113]
	ds_read_b128 v[34:37], v69 offset:20224
	ds_read_b128 v[78:81], v69 offset:20736
	ds_read_b64 v[108:109], v118 offset:21248
	ds_read_b128 v[30:33], v69 offset:19968
	ds_read_b128 v[74:77], v69 offset:20480
	ds_read_b128 v[104:107], v69 offset:20992
	v_add_f32_e32 v70, v110, v111
	v_add_f32_e32 v72, v112, v113
	v_pk_mul_f32 v[38:39], v[20:21], v[28:29] op_sel_hi:[1,0]
	v_add_f32_dpp v70, v70, v70 row_ror:8 row_mask:0xf bank_mask:0xf bound_ctrl:1
	v_add_f32_dpp v72, v72, v72 row_ror:8 row_mask:0xf bank_mask:0xf bound_ctrl:1
	v_pk_mul_f32 v[82:83], v[22:23], v[28:29] op_sel_hi:[1,0]
	v_add_f32_dpp v70, v70, v70 row_ror:4 row_mask:0xf bank_mask:0xf bound_ctrl:1
	v_add_f32_dpp v72, v72, v72 row_ror:4 row_mask:0xf bank_mask:0xf bound_ctrl:1
	v_pk_mul_f32 v[116:117], v[20:21], v[28:29] op_sel:[0,1] op_sel_hi:[1,1]
	v_add_f32_dpp v70, v70, v70 row_ror:2 row_mask:0xf bank_mask:0xf bound_ctrl:1
	v_add_f32_dpp v72, v72, v72 row_ror:2 row_mask:0xf bank_mask:0xf bound_ctrl:1
	v_pk_mul_f32 v[114:115], v[22:23], v[28:29] op_sel:[0,1] op_sel_hi:[1,1]
	v_add_f32_dpp v70, v70, v70 row_ror:1 row_mask:0xf bank_mask:0xf bound_ctrl:1
	v_add_f32_dpp v72, v72, v72 row_ror:1 row_mask:0xf bank_mask:0xf bound_ctrl:1
	v_pk_fma_f32 v[38:39], v[0:1], v[8:9], v[38:39]
	v_pk_fma_f32 v[82:83], v[2:3], v[10:11], v[82:83]
	v_pk_fma_f32 v[116:117], v[4:5], v[8:9], v[116:117]
	v_pk_fma_f32 v[114:115], v[6:7], v[10:11], v[114:115]
	v_pk_fma_f32 v[0:1], v[16:17], v[70:71], v[38:39] op_sel_hi:[1,0,1]
	v_pk_fma_f32 v[2:3], v[18:19], v[70:71], v[82:83] op_sel_hi:[1,0,1]
	v_pk_fma_f32 v[4:5], v[16:17], v[72:73], v[116:117] op_sel_hi:[1,0,1]
	v_pk_fma_f32 v[6:7], v[18:19], v[72:73], v[114:115] op_sel_hi:[1,0,1]
	v_pk_mul_f32 v[110:111], v[2:3], v[26:27]
	v_pk_mul_f32 v[112:113], v[6:7], v[26:27]
	v_pk_fma_f32 v[110:111], v[0:1], v[24:25], v[110:111]
	v_pk_fma_f32 v[112:113], v[4:5], v[24:25], v[112:113]
	v_add_f32_e32 v110, v110, v111
	v_add_f32_e32 v112, v112, v113
	ds_write_b32 v119, v110 offset:24576
	ds_write_b32 v119, v112 offset:24640
	s_waitcnt lgkmcnt(2)
	v_pk_mul_f32 v[110:111], v[2:3], v[36:37]
	v_pk_mul_f32 v[112:113], v[6:7], v[36:37]
	v_pk_fma_f32 v[110:111], v[0:1], v[34:35], v[110:111]
	v_pk_fma_f32 v[112:113], v[4:5], v[34:35], v[112:113]
	ds_read_b128 v[12:15], v69 offset:21760
	ds_read_b128 v[20:23], v69 offset:22272
	ds_read_b64 v[28:29], v118 offset:22784
	ds_read_b128 v[8:11], v69 offset:21504
	ds_read_b128 v[16:19], v69 offset:22016
	ds_read_b128 v[24:27], v69 offset:22528
	v_add_f32_e32 v70, v110, v111
	v_add_f32_e32 v72, v112, v113
	v_pk_mul_f32 v[38:39], v[78:79], v[108:109] op_sel_hi:[1,0]
	v_add_f32_dpp v70, v70, v70 row_ror:8 row_mask:0xf bank_mask:0xf bound_ctrl:1
	v_add_f32_dpp v72, v72, v72 row_ror:8 row_mask:0xf bank_mask:0xf bound_ctrl:1
	v_pk_mul_f32 v[82:83], v[80:81], v[108:109] op_sel_hi:[1,0]
	v_add_f32_dpp v70, v70, v70 row_ror:4 row_mask:0xf bank_mask:0xf bound_ctrl:1
	v_add_f32_dpp v72, v72, v72 row_ror:4 row_mask:0xf bank_mask:0xf bound_ctrl:1
	v_pk_mul_f32 v[116:117], v[78:79], v[108:109] op_sel:[0,1] op_sel_hi:[1,1]
	v_add_f32_dpp v70, v70, v70 row_ror:2 row_mask:0xf bank_mask:0xf bound_ctrl:1
	v_add_f32_dpp v72, v72, v72 row_ror:2 row_mask:0xf bank_mask:0xf bound_ctrl:1
	v_pk_mul_f32 v[114:115], v[80:81], v[108:109] op_sel:[0,1] op_sel_hi:[1,1]
	v_add_f32_dpp v70, v70, v70 row_ror:1 row_mask:0xf bank_mask:0xf bound_ctrl:1
	v_add_f32_dpp v72, v72, v72 row_ror:1 row_mask:0xf bank_mask:0xf bound_ctrl:1
	v_pk_fma_f32 v[38:39], v[0:1], v[30:31], v[38:39]
	v_pk_fma_f32 v[82:83], v[2:3], v[32:33], v[82:83]
	v_pk_fma_f32 v[116:117], v[4:5], v[30:31], v[116:117]
	v_pk_fma_f32 v[114:115], v[6:7], v[32:33], v[114:115]
	v_pk_fma_f32 v[0:1], v[74:75], v[70:71], v[38:39] op_sel_hi:[1,0,1]
	v_pk_fma_f32 v[2:3], v[76:77], v[70:71], v[82:83] op_sel_hi:[1,0,1]
	v_pk_fma_f32 v[4:5], v[74:75], v[72:73], v[116:117] op_sel_hi:[1,0,1]
	v_pk_fma_f32 v[6:7], v[76:77], v[72:73], v[114:115] op_sel_hi:[1,0,1]
	v_pk_mul_f32 v[110:111], v[2:3], v[106:107]
	v_pk_mul_f32 v[112:113], v[6:7], v[106:107]
	v_pk_fma_f32 v[110:111], v[0:1], v[104:105], v[110:111]
	v_pk_fma_f32 v[112:113], v[4:5], v[104:105], v[112:113]
	v_add_f32_e32 v110, v110, v111
	v_add_f32_e32 v112, v112, v113
	ds_write_b32 v119, v110 offset:26624
	ds_write_b32 v119, v112 offset:26688
	s_waitcnt lgkmcnt(2)
	v_pk_mul_f32 v[110:111], v[2:3], v[14:15]
	v_pk_mul_f32 v[112:113], v[6:7], v[14:15]
	v_pk_fma_f32 v[110:111], v[0:1], v[12:13], v[110:111]
	v_pk_fma_f32 v[112:113], v[4:5], v[12:13], v[112:113]
	ds_read_b128 v[34:37], v69 offset:23296
	ds_read_b128 v[78:81], v69 offset:23808
	ds_read_b64 v[108:109], v118 offset:24320
	ds_read_b128 v[30:33], v69 offset:23040
	ds_read_b128 v[74:77], v69 offset:23552
	ds_read_b128 v[104:107], v69 offset:24064
	v_add_f32_e32 v70, v110, v111
	v_add_f32_e32 v72, v112, v113
	v_pk_mul_f32 v[38:39], v[20:21], v[28:29] op_sel_hi:[1,0]
	v_add_f32_dpp v70, v70, v70 row_ror:8 row_mask:0xf bank_mask:0xf bound_ctrl:1
	v_add_f32_dpp v72, v72, v72 row_ror:8 row_mask:0xf bank_mask:0xf bound_ctrl:1
	v_pk_mul_f32 v[82:83], v[22:23], v[28:29] op_sel_hi:[1,0]
	v_add_f32_dpp v70, v70, v70 row_ror:4 row_mask:0xf bank_mask:0xf bound_ctrl:1
	v_add_f32_dpp v72, v72, v72 row_ror:4 row_mask:0xf bank_mask:0xf bound_ctrl:1
	v_pk_mul_f32 v[116:117], v[20:21], v[28:29] op_sel:[0,1] op_sel_hi:[1,1]
	v_add_f32_dpp v70, v70, v70 row_ror:2 row_mask:0xf bank_mask:0xf bound_ctrl:1
	v_add_f32_dpp v72, v72, v72 row_ror:2 row_mask:0xf bank_mask:0xf bound_ctrl:1
	v_pk_mul_f32 v[114:115], v[22:23], v[28:29] op_sel:[0,1] op_sel_hi:[1,1]
	v_add_f32_dpp v70, v70, v70 row_ror:1 row_mask:0xf bank_mask:0xf bound_ctrl:1
	v_add_f32_dpp v72, v72, v72 row_ror:1 row_mask:0xf bank_mask:0xf bound_ctrl:1
	v_pk_fma_f32 v[38:39], v[0:1], v[8:9], v[38:39]
	v_pk_fma_f32 v[82:83], v[2:3], v[10:11], v[82:83]
	v_pk_fma_f32 v[116:117], v[4:5], v[8:9], v[116:117]
	v_pk_fma_f32 v[114:115], v[6:7], v[10:11], v[114:115]
	v_pk_fma_f32 v[0:1], v[16:17], v[70:71], v[38:39] op_sel_hi:[1,0,1]
	v_pk_fma_f32 v[2:3], v[18:19], v[70:71], v[82:83] op_sel_hi:[1,0,1]
	v_pk_fma_f32 v[4:5], v[16:17], v[72:73], v[116:117] op_sel_hi:[1,0,1]
	v_pk_fma_f32 v[6:7], v[18:19], v[72:73], v[114:115] op_sel_hi:[1,0,1]
	v_pk_mul_f32 v[110:111], v[2:3], v[26:27]
	v_pk_mul_f32 v[112:113], v[6:7], v[26:27]
	v_pk_fma_f32 v[110:111], v[0:1], v[24:25], v[110:111]
	v_pk_fma_f32 v[112:113], v[4:5], v[24:25], v[112:113]
	v_add_f32_e32 v110, v110, v111
	v_add_f32_e32 v112, v112, v113
	ds_write_b32 v119, v110 offset:28672
	ds_write_b32 v119, v112 offset:28736
	s_waitcnt lgkmcnt(2)
	v_pk_mul_f32 v[110:111], v[2:3], v[36:37]
	v_pk_mul_f32 v[112:113], v[6:7], v[36:37]
	v_pk_fma_f32 v[110:111], v[0:1], v[34:35], v[110:111]
	v_pk_fma_f32 v[112:113], v[4:5], v[34:35], v[112:113]
	v_add_f32_e32 v70, v110, v111
	v_add_f32_e32 v72, v112, v113
	v_pk_mul_f32 v[38:39], v[78:79], v[108:109] op_sel_hi:[1,0]
	v_add_f32_dpp v70, v70, v70 row_ror:8 row_mask:0xf bank_mask:0xf bound_ctrl:1
	v_add_f32_dpp v72, v72, v72 row_ror:8 row_mask:0xf bank_mask:0xf bound_ctrl:1
	v_pk_mul_f32 v[82:83], v[80:81], v[108:109] op_sel_hi:[1,0]
	v_add_f32_dpp v70, v70, v70 row_ror:4 row_mask:0xf bank_mask:0xf bound_ctrl:1
	v_add_f32_dpp v72, v72, v72 row_ror:4 row_mask:0xf bank_mask:0xf bound_ctrl:1
	v_pk_mul_f32 v[116:117], v[78:79], v[108:109] op_sel:[0,1] op_sel_hi:[1,1]
	v_add_f32_dpp v70, v70, v70 row_ror:2 row_mask:0xf bank_mask:0xf bound_ctrl:1
	v_add_f32_dpp v72, v72, v72 row_ror:2 row_mask:0xf bank_mask:0xf bound_ctrl:1
	v_pk_mul_f32 v[114:115], v[80:81], v[108:109] op_sel:[0,1] op_sel_hi:[1,1]
	v_add_f32_dpp v70, v70, v70 row_ror:1 row_mask:0xf bank_mask:0xf bound_ctrl:1
	v_add_f32_dpp v72, v72, v72 row_ror:1 row_mask:0xf bank_mask:0xf bound_ctrl:1
	v_pk_fma_f32 v[38:39], v[0:1], v[30:31], v[38:39]
	v_pk_fma_f32 v[82:83], v[2:3], v[32:33], v[82:83]
	v_pk_fma_f32 v[116:117], v[4:5], v[30:31], v[116:117]
	v_pk_fma_f32 v[114:115], v[6:7], v[32:33], v[114:115]
	v_pk_fma_f32 v[0:1], v[74:75], v[70:71], v[38:39] op_sel_hi:[1,0,1]
	v_pk_fma_f32 v[2:3], v[76:77], v[70:71], v[82:83] op_sel_hi:[1,0,1]
	v_pk_fma_f32 v[4:5], v[74:75], v[72:73], v[116:117] op_sel_hi:[1,0,1]
	v_pk_fma_f32 v[6:7], v[76:77], v[72:73], v[114:115] op_sel_hi:[1,0,1]
	v_pk_mul_f32 v[110:111], v[2:3], v[106:107]
	v_pk_mul_f32 v[112:113], v[6:7], v[106:107]
	v_pk_fma_f32 v[110:111], v[0:1], v[104:105], v[110:111]
	v_pk_fma_f32 v[112:113], v[4:5], v[104:105], v[112:113]
	v_add_f32_e32 v110, v110, v111
	v_add_f32_e32 v112, v112, v113
	ds_write_b32 v119, v110 offset:30720
	ds_write_b32 v119, v112 offset:30784
	s_waitcnt lgkmcnt(0)
	s_barrier
	ds_read_b128 v[12:15], v69 offset:24832
	ds_read_b128 v[20:23], v69 offset:25344
	ds_read_b64 v[28:29], v118 offset:25856
	ds_read_b128 v[8:11], v69 offset:24576
	ds_read_b128 v[16:19], v69 offset:25088
	ds_read_b128 v[24:27], v69 offset:25600
	s_waitcnt lgkmcnt(0)
	v_pk_mul_f32 v[110:111], v[2:3], v[14:15]
	v_pk_mul_f32 v[112:113], v[6:7], v[14:15]
	v_pk_fma_f32 v[110:111], v[0:1], v[12:13], v[110:111]
	v_pk_fma_f32 v[112:113], v[4:5], v[12:13], v[112:113]
	ds_read_b128 v[34:37], v69 offset:26368
	ds_read_b128 v[78:81], v69 offset:26880
	ds_read_b64 v[108:109], v118 offset:27392
	ds_read_b128 v[30:33], v69 offset:26112
	ds_read_b128 v[74:77], v69 offset:26624
	ds_read_b128 v[104:107], v69 offset:27136
	v_add_f32_e32 v70, v110, v111
	v_add_f32_e32 v72, v112, v113
	v_pk_mul_f32 v[38:39], v[20:21], v[28:29] op_sel_hi:[1,0]
	v_add_f32_dpp v70, v70, v70 row_ror:8 row_mask:0xf bank_mask:0xf bound_ctrl:1
	v_add_f32_dpp v72, v72, v72 row_ror:8 row_mask:0xf bank_mask:0xf bound_ctrl:1
	v_pk_mul_f32 v[82:83], v[22:23], v[28:29] op_sel_hi:[1,0]
	v_add_f32_dpp v70, v70, v70 row_ror:4 row_mask:0xf bank_mask:0xf bound_ctrl:1
	v_add_f32_dpp v72, v72, v72 row_ror:4 row_mask:0xf bank_mask:0xf bound_ctrl:1
	v_pk_mul_f32 v[116:117], v[20:21], v[28:29] op_sel:[0,1] op_sel_hi:[1,1]
	v_add_f32_dpp v70, v70, v70 row_ror:2 row_mask:0xf bank_mask:0xf bound_ctrl:1
	v_add_f32_dpp v72, v72, v72 row_ror:2 row_mask:0xf bank_mask:0xf bound_ctrl:1
	v_pk_mul_f32 v[114:115], v[22:23], v[28:29] op_sel:[0,1] op_sel_hi:[1,1]
	v_add_f32_dpp v70, v70, v70 row_ror:1 row_mask:0xf bank_mask:0xf bound_ctrl:1
	v_add_f32_dpp v72, v72, v72 row_ror:1 row_mask:0xf bank_mask:0xf bound_ctrl:1
	v_pk_fma_f32 v[38:39], v[0:1], v[8:9], v[38:39]
	v_pk_fma_f32 v[82:83], v[2:3], v[10:11], v[82:83]
	v_pk_fma_f32 v[116:117], v[4:5], v[8:9], v[116:117]
	v_pk_fma_f32 v[114:115], v[6:7], v[10:11], v[114:115]
	v_pk_fma_f32 v[0:1], v[16:17], v[70:71], v[38:39] op_sel_hi:[1,0,1]
	v_pk_fma_f32 v[2:3], v[18:19], v[70:71], v[82:83] op_sel_hi:[1,0,1]
	v_pk_fma_f32 v[4:5], v[16:17], v[72:73], v[116:117] op_sel_hi:[1,0,1]
	v_pk_fma_f32 v[6:7], v[18:19], v[72:73], v[114:115] op_sel_hi:[1,0,1]
	v_pk_mul_f32 v[110:111], v[2:3], v[26:27]
	v_pk_mul_f32 v[112:113], v[6:7], v[26:27]
	v_pk_fma_f32 v[110:111], v[0:1], v[24:25], v[110:111]
	v_pk_fma_f32 v[112:113], v[4:5], v[24:25], v[112:113]
	v_add_f32_e32 v110, v110, v111
	v_add_f32_e32 v112, v112, v113
	ds_write_b32 v119, v110 offset:0
	ds_write_b32 v119, v112 offset:64
	s_waitcnt lgkmcnt(2)
	v_pk_mul_f32 v[110:111], v[2:3], v[36:37]
	v_pk_mul_f32 v[112:113], v[6:7], v[36:37]
	v_pk_fma_f32 v[110:111], v[0:1], v[34:35], v[110:111]
	v_pk_fma_f32 v[112:113], v[4:5], v[34:35], v[112:113]
	ds_read_b128 v[12:15], v69 offset:27904
	ds_read_b128 v[20:23], v69 offset:28416
	ds_read_b64 v[28:29], v118 offset:28928
	ds_read_b128 v[8:11], v69 offset:27648
	ds_read_b128 v[16:19], v69 offset:28160
	ds_read_b128 v[24:27], v69 offset:28672
	v_add_f32_e32 v70, v110, v111
	v_add_f32_e32 v72, v112, v113
	v_pk_mul_f32 v[38:39], v[78:79], v[108:109] op_sel_hi:[1,0]
	v_add_f32_dpp v70, v70, v70 row_ror:8 row_mask:0xf bank_mask:0xf bound_ctrl:1
	v_add_f32_dpp v72, v72, v72 row_ror:8 row_mask:0xf bank_mask:0xf bound_ctrl:1
	v_pk_mul_f32 v[82:83], v[80:81], v[108:109] op_sel_hi:[1,0]
	v_add_f32_dpp v70, v70, v70 row_ror:4 row_mask:0xf bank_mask:0xf bound_ctrl:1
	v_add_f32_dpp v72, v72, v72 row_ror:4 row_mask:0xf bank_mask:0xf bound_ctrl:1
	v_pk_mul_f32 v[116:117], v[78:79], v[108:109] op_sel:[0,1] op_sel_hi:[1,1]
	v_add_f32_dpp v70, v70, v70 row_ror:2 row_mask:0xf bank_mask:0xf bound_ctrl:1
	v_add_f32_dpp v72, v72, v72 row_ror:2 row_mask:0xf bank_mask:0xf bound_ctrl:1
	v_pk_mul_f32 v[114:115], v[80:81], v[108:109] op_sel:[0,1] op_sel_hi:[1,1]
	v_add_f32_dpp v70, v70, v70 row_ror:1 row_mask:0xf bank_mask:0xf bound_ctrl:1
	v_add_f32_dpp v72, v72, v72 row_ror:1 row_mask:0xf bank_mask:0xf bound_ctrl:1
	v_pk_fma_f32 v[38:39], v[0:1], v[30:31], v[38:39]
	v_pk_fma_f32 v[82:83], v[2:3], v[32:33], v[82:83]
	v_pk_fma_f32 v[116:117], v[4:5], v[30:31], v[116:117]
	v_pk_fma_f32 v[114:115], v[6:7], v[32:33], v[114:115]
	v_pk_fma_f32 v[0:1], v[74:75], v[70:71], v[38:39] op_sel_hi:[1,0,1]
	v_pk_fma_f32 v[2:3], v[76:77], v[70:71], v[82:83] op_sel_hi:[1,0,1]
	v_pk_fma_f32 v[4:5], v[74:75], v[72:73], v[116:117] op_sel_hi:[1,0,1]
	v_pk_fma_f32 v[6:7], v[76:77], v[72:73], v[114:115] op_sel_hi:[1,0,1]
	v_pk_mul_f32 v[110:111], v[2:3], v[106:107]
	v_pk_mul_f32 v[112:113], v[6:7], v[106:107]
	v_pk_fma_f32 v[110:111], v[0:1], v[104:105], v[110:111]
	v_pk_fma_f32 v[112:113], v[4:5], v[104:105], v[112:113]
	v_add_f32_e32 v110, v110, v111
	v_add_f32_e32 v112, v112, v113
	ds_write_b32 v119, v110 offset:2048
	ds_write_b32 v119, v112 offset:2112
	s_waitcnt lgkmcnt(2)
	v_pk_mul_f32 v[110:111], v[2:3], v[14:15]
	v_pk_mul_f32 v[112:113], v[6:7], v[14:15]
	v_pk_fma_f32 v[110:111], v[0:1], v[12:13], v[110:111]
	v_pk_fma_f32 v[112:113], v[4:5], v[12:13], v[112:113]
	ds_read_b128 v[34:37], v69 offset:29440
	ds_read_b128 v[78:81], v69 offset:29952
	ds_read_b64 v[108:109], v118 offset:30464
	ds_read_b128 v[30:33], v69 offset:29184
	ds_read_b128 v[74:77], v69 offset:29696
	ds_read_b128 v[104:107], v69 offset:30208
	v_add_f32_e32 v70, v110, v111
	v_add_f32_e32 v72, v112, v113
	v_pk_mul_f32 v[38:39], v[20:21], v[28:29] op_sel_hi:[1,0]
	v_add_f32_dpp v70, v70, v70 row_ror:8 row_mask:0xf bank_mask:0xf bound_ctrl:1
	v_add_f32_dpp v72, v72, v72 row_ror:8 row_mask:0xf bank_mask:0xf bound_ctrl:1
	v_pk_mul_f32 v[82:83], v[22:23], v[28:29] op_sel_hi:[1,0]
	v_add_f32_dpp v70, v70, v70 row_ror:4 row_mask:0xf bank_mask:0xf bound_ctrl:1
	v_add_f32_dpp v72, v72, v72 row_ror:4 row_mask:0xf bank_mask:0xf bound_ctrl:1
	v_pk_mul_f32 v[116:117], v[20:21], v[28:29] op_sel:[0,1] op_sel_hi:[1,1]
	v_add_f32_dpp v70, v70, v70 row_ror:2 row_mask:0xf bank_mask:0xf bound_ctrl:1
	v_add_f32_dpp v72, v72, v72 row_ror:2 row_mask:0xf bank_mask:0xf bound_ctrl:1
	v_pk_mul_f32 v[114:115], v[22:23], v[28:29] op_sel:[0,1] op_sel_hi:[1,1]
	v_add_f32_dpp v70, v70, v70 row_ror:1 row_mask:0xf bank_mask:0xf bound_ctrl:1
	v_add_f32_dpp v72, v72, v72 row_ror:1 row_mask:0xf bank_mask:0xf bound_ctrl:1
	v_pk_fma_f32 v[38:39], v[0:1], v[8:9], v[38:39]
	v_pk_fma_f32 v[82:83], v[2:3], v[10:11], v[82:83]
	v_pk_fma_f32 v[116:117], v[4:5], v[8:9], v[116:117]
	v_pk_fma_f32 v[114:115], v[6:7], v[10:11], v[114:115]
	v_pk_fma_f32 v[0:1], v[16:17], v[70:71], v[38:39] op_sel_hi:[1,0,1]
	v_pk_fma_f32 v[2:3], v[18:19], v[70:71], v[82:83] op_sel_hi:[1,0,1]
	v_pk_fma_f32 v[4:5], v[16:17], v[72:73], v[116:117] op_sel_hi:[1,0,1]
	v_pk_fma_f32 v[6:7], v[18:19], v[72:73], v[114:115] op_sel_hi:[1,0,1]
	v_pk_mul_f32 v[110:111], v[2:3], v[26:27]
	v_pk_mul_f32 v[112:113], v[6:7], v[26:27]
	v_pk_fma_f32 v[110:111], v[0:1], v[24:25], v[110:111]
	v_pk_fma_f32 v[112:113], v[4:5], v[24:25], v[112:113]
	v_add_f32_e32 v110, v110, v111
	v_add_f32_e32 v112, v112, v113
	ds_write_b32 v119, v110 offset:4096
	ds_write_b32 v119, v112 offset:4160
	s_waitcnt lgkmcnt(2)
	v_pk_mul_f32 v[110:111], v[2:3], v[36:37]
	v_pk_mul_f32 v[112:113], v[6:7], v[36:37]
	v_pk_fma_f32 v[110:111], v[0:1], v[34:35], v[110:111]
	v_pk_fma_f32 v[112:113], v[4:5], v[34:35], v[112:113]
	ds_read_b128 v[12:15], v69 offset:30976
	ds_read_b128 v[20:23], v69 offset:31488
	ds_read_b64 v[28:29], v118 offset:32000
	ds_read_b128 v[8:11], v69 offset:30720
	ds_read_b128 v[16:19], v69 offset:31232
	ds_read_b128 v[24:27], v69 offset:31744
	v_add_f32_e32 v70, v110, v111
	v_add_f32_e32 v72, v112, v113
	v_pk_mul_f32 v[38:39], v[78:79], v[108:109] op_sel_hi:[1,0]
	v_add_f32_dpp v70, v70, v70 row_ror:8 row_mask:0xf bank_mask:0xf bound_ctrl:1
	v_add_f32_dpp v72, v72, v72 row_ror:8 row_mask:0xf bank_mask:0xf bound_ctrl:1
	v_pk_mul_f32 v[82:83], v[80:81], v[108:109] op_sel_hi:[1,0]
	v_add_f32_dpp v70, v70, v70 row_ror:4 row_mask:0xf bank_mask:0xf bound_ctrl:1
	v_add_f32_dpp v72, v72, v72 row_ror:4 row_mask:0xf bank_mask:0xf bound_ctrl:1
	v_pk_mul_f32 v[116:117], v[78:79], v[108:109] op_sel:[0,1] op_sel_hi:[1,1]
	v_add_f32_dpp v70, v70, v70 row_ror:2 row_mask:0xf bank_mask:0xf bound_ctrl:1
	v_add_f32_dpp v72, v72, v72 row_ror:2 row_mask:0xf bank_mask:0xf bound_ctrl:1
	v_pk_mul_f32 v[114:115], v[80:81], v[108:109] op_sel:[0,1] op_sel_hi:[1,1]
	v_add_f32_dpp v70, v70, v70 row_ror:1 row_mask:0xf bank_mask:0xf bound_ctrl:1
	v_add_f32_dpp v72, v72, v72 row_ror:1 row_mask:0xf bank_mask:0xf bound_ctrl:1
	v_pk_fma_f32 v[38:39], v[0:1], v[30:31], v[38:39]
	v_pk_fma_f32 v[82:83], v[2:3], v[32:33], v[82:83]
	v_pk_fma_f32 v[116:117], v[4:5], v[30:31], v[116:117]
	v_pk_fma_f32 v[114:115], v[6:7], v[32:33], v[114:115]
	v_pk_fma_f32 v[0:1], v[74:75], v[70:71], v[38:39] op_sel_hi:[1,0,1]
	v_pk_fma_f32 v[2:3], v[76:77], v[70:71], v[82:83] op_sel_hi:[1,0,1]
	v_pk_fma_f32 v[4:5], v[74:75], v[72:73], v[116:117] op_sel_hi:[1,0,1]
	v_pk_fma_f32 v[6:7], v[76:77], v[72:73], v[114:115] op_sel_hi:[1,0,1]
	v_pk_mul_f32 v[110:111], v[2:3], v[106:107]
	v_pk_mul_f32 v[112:113], v[6:7], v[106:107]
	v_pk_fma_f32 v[110:111], v[0:1], v[104:105], v[110:111]
	v_pk_fma_f32 v[112:113], v[4:5], v[104:105], v[112:113]
	v_add_f32_e32 v110, v110, v111
	v_add_f32_e32 v112, v112, v113
	ds_write_b32 v119, v110 offset:6144
	ds_write_b32 v119, v112 offset:6208
	s_waitcnt lgkmcnt(2)
	v_pk_mul_f32 v[110:111], v[2:3], v[14:15]
	v_pk_mul_f32 v[112:113], v[6:7], v[14:15]
	v_pk_fma_f32 v[110:111], v[0:1], v[12:13], v[110:111]
	v_pk_fma_f32 v[112:113], v[4:5], v[12:13], v[112:113]
	ds_read_b128 v[34:37], v69 offset:32512
	ds_read_b128 v[78:81], v69 offset:33024
	ds_read_b64 v[108:109], v118 offset:33536
	ds_read_b128 v[30:33], v69 offset:32256
	ds_read_b128 v[74:77], v69 offset:32768
	ds_read_b128 v[104:107], v69 offset:33280
	v_add_f32_e32 v70, v110, v111
	v_add_f32_e32 v72, v112, v113
	v_pk_mul_f32 v[38:39], v[20:21], v[28:29] op_sel_hi:[1,0]
	v_add_f32_dpp v70, v70, v70 row_ror:8 row_mask:0xf bank_mask:0xf bound_ctrl:1
	v_add_f32_dpp v72, v72, v72 row_ror:8 row_mask:0xf bank_mask:0xf bound_ctrl:1
	v_pk_mul_f32 v[82:83], v[22:23], v[28:29] op_sel_hi:[1,0]
	v_add_f32_dpp v70, v70, v70 row_ror:4 row_mask:0xf bank_mask:0xf bound_ctrl:1
	v_add_f32_dpp v72, v72, v72 row_ror:4 row_mask:0xf bank_mask:0xf bound_ctrl:1
	v_pk_mul_f32 v[116:117], v[20:21], v[28:29] op_sel:[0,1] op_sel_hi:[1,1]
	v_add_f32_dpp v70, v70, v70 row_ror:2 row_mask:0xf bank_mask:0xf bound_ctrl:1
	v_add_f32_dpp v72, v72, v72 row_ror:2 row_mask:0xf bank_mask:0xf bound_ctrl:1
	v_pk_mul_f32 v[114:115], v[22:23], v[28:29] op_sel:[0,1] op_sel_hi:[1,1]
	v_add_f32_dpp v70, v70, v70 row_ror:1 row_mask:0xf bank_mask:0xf bound_ctrl:1
	v_add_f32_dpp v72, v72, v72 row_ror:1 row_mask:0xf bank_mask:0xf bound_ctrl:1
	v_pk_fma_f32 v[38:39], v[0:1], v[8:9], v[38:39]
	v_pk_fma_f32 v[82:83], v[2:3], v[10:11], v[82:83]
	v_pk_fma_f32 v[116:117], v[4:5], v[8:9], v[116:117]
	v_pk_fma_f32 v[114:115], v[6:7], v[10:11], v[114:115]
	v_pk_fma_f32 v[0:1], v[16:17], v[70:71], v[38:39] op_sel_hi:[1,0,1]
	v_pk_fma_f32 v[2:3], v[18:19], v[70:71], v[82:83] op_sel_hi:[1,0,1]
	v_pk_fma_f32 v[4:5], v[16:17], v[72:73], v[116:117] op_sel_hi:[1,0,1]
	v_pk_fma_f32 v[6:7], v[18:19], v[72:73], v[114:115] op_sel_hi:[1,0,1]
	v_pk_mul_f32 v[110:111], v[2:3], v[26:27]
	v_pk_mul_f32 v[112:113], v[6:7], v[26:27]
	v_pk_fma_f32 v[110:111], v[0:1], v[24:25], v[110:111]
	v_pk_fma_f32 v[112:113], v[4:5], v[24:25], v[112:113]
	v_add_f32_e32 v110, v110, v111
	v_add_f32_e32 v112, v112, v113
	ds_write_b32 v119, v110 offset:8192
	ds_write_b32 v119, v112 offset:8256
	s_waitcnt lgkmcnt(2)
	v_pk_mul_f32 v[110:111], v[2:3], v[36:37]
	v_pk_mul_f32 v[112:113], v[6:7], v[36:37]
	v_pk_fma_f32 v[110:111], v[0:1], v[34:35], v[110:111]
	v_pk_fma_f32 v[112:113], v[4:5], v[34:35], v[112:113]
	ds_read_b128 v[12:15], v69 offset:34048
	ds_read_b128 v[20:23], v69 offset:34560
	ds_read_b64 v[28:29], v118 offset:35072
	ds_read_b128 v[8:11], v69 offset:33792
	ds_read_b128 v[16:19], v69 offset:34304
	ds_read_b128 v[24:27], v69 offset:34816
	v_add_f32_e32 v70, v110, v111
	v_add_f32_e32 v72, v112, v113
	v_pk_mul_f32 v[38:39], v[78:79], v[108:109] op_sel_hi:[1,0]
	v_add_f32_dpp v70, v70, v70 row_ror:8 row_mask:0xf bank_mask:0xf bound_ctrl:1
	v_add_f32_dpp v72, v72, v72 row_ror:8 row_mask:0xf bank_mask:0xf bound_ctrl:1
	v_pk_mul_f32 v[82:83], v[80:81], v[108:109] op_sel_hi:[1,0]
	v_add_f32_dpp v70, v70, v70 row_ror:4 row_mask:0xf bank_mask:0xf bound_ctrl:1
	v_add_f32_dpp v72, v72, v72 row_ror:4 row_mask:0xf bank_mask:0xf bound_ctrl:1
	v_pk_mul_f32 v[116:117], v[78:79], v[108:109] op_sel:[0,1] op_sel_hi:[1,1]
	v_add_f32_dpp v70, v70, v70 row_ror:2 row_mask:0xf bank_mask:0xf bound_ctrl:1
	v_add_f32_dpp v72, v72, v72 row_ror:2 row_mask:0xf bank_mask:0xf bound_ctrl:1
	v_pk_mul_f32 v[114:115], v[80:81], v[108:109] op_sel:[0,1] op_sel_hi:[1,1]
	v_add_f32_dpp v70, v70, v70 row_ror:1 row_mask:0xf bank_mask:0xf bound_ctrl:1
	v_add_f32_dpp v72, v72, v72 row_ror:1 row_mask:0xf bank_mask:0xf bound_ctrl:1
	v_pk_fma_f32 v[38:39], v[0:1], v[30:31], v[38:39]
	v_pk_fma_f32 v[82:83], v[2:3], v[32:33], v[82:83]
	v_pk_fma_f32 v[116:117], v[4:5], v[30:31], v[116:117]
	v_pk_fma_f32 v[114:115], v[6:7], v[32:33], v[114:115]
	v_pk_fma_f32 v[0:1], v[74:75], v[70:71], v[38:39] op_sel_hi:[1,0,1]
	v_pk_fma_f32 v[2:3], v[76:77], v[70:71], v[82:83] op_sel_hi:[1,0,1]
	v_pk_fma_f32 v[4:5], v[74:75], v[72:73], v[116:117] op_sel_hi:[1,0,1]
	v_pk_fma_f32 v[6:7], v[76:77], v[72:73], v[114:115] op_sel_hi:[1,0,1]
	v_pk_mul_f32 v[110:111], v[2:3], v[106:107]
	v_pk_mul_f32 v[112:113], v[6:7], v[106:107]
	v_pk_fma_f32 v[110:111], v[0:1], v[104:105], v[110:111]
	v_pk_fma_f32 v[112:113], v[4:5], v[104:105], v[112:113]
	v_add_f32_e32 v110, v110, v111
	v_add_f32_e32 v112, v112, v113
	ds_write_b32 v119, v110 offset:10240
	ds_write_b32 v119, v112 offset:10304
	s_waitcnt lgkmcnt(2)
	v_pk_mul_f32 v[110:111], v[2:3], v[14:15]
	v_pk_mul_f32 v[112:113], v[6:7], v[14:15]
	v_pk_fma_f32 v[110:111], v[0:1], v[12:13], v[110:111]
	v_pk_fma_f32 v[112:113], v[4:5], v[12:13], v[112:113]
	ds_read_b128 v[34:37], v69 offset:35584
	ds_read_b128 v[78:81], v69 offset:36096
	ds_read_b64 v[108:109], v118 offset:36608
	ds_read_b128 v[30:33], v69 offset:35328
	ds_read_b128 v[74:77], v69 offset:35840
	ds_read_b128 v[104:107], v69 offset:36352
	v_add_f32_e32 v70, v110, v111
	v_add_f32_e32 v72, v112, v113
	v_pk_mul_f32 v[38:39], v[20:21], v[28:29] op_sel_hi:[1,0]
	v_add_f32_dpp v70, v70, v70 row_ror:8 row_mask:0xf bank_mask:0xf bound_ctrl:1
	v_add_f32_dpp v72, v72, v72 row_ror:8 row_mask:0xf bank_mask:0xf bound_ctrl:1
	v_pk_mul_f32 v[82:83], v[22:23], v[28:29] op_sel_hi:[1,0]
	v_add_f32_dpp v70, v70, v70 row_ror:4 row_mask:0xf bank_mask:0xf bound_ctrl:1
	v_add_f32_dpp v72, v72, v72 row_ror:4 row_mask:0xf bank_mask:0xf bound_ctrl:1
	v_pk_mul_f32 v[116:117], v[20:21], v[28:29] op_sel:[0,1] op_sel_hi:[1,1]
	v_add_f32_dpp v70, v70, v70 row_ror:2 row_mask:0xf bank_mask:0xf bound_ctrl:1
	v_add_f32_dpp v72, v72, v72 row_ror:2 row_mask:0xf bank_mask:0xf bound_ctrl:1
	v_pk_mul_f32 v[114:115], v[22:23], v[28:29] op_sel:[0,1] op_sel_hi:[1,1]
	v_add_f32_dpp v70, v70, v70 row_ror:1 row_mask:0xf bank_mask:0xf bound_ctrl:1
	v_add_f32_dpp v72, v72, v72 row_ror:1 row_mask:0xf bank_mask:0xf bound_ctrl:1
	v_pk_fma_f32 v[38:39], v[0:1], v[8:9], v[38:39]
	v_pk_fma_f32 v[82:83], v[2:3], v[10:11], v[82:83]
	v_pk_fma_f32 v[116:117], v[4:5], v[8:9], v[116:117]
	v_pk_fma_f32 v[114:115], v[6:7], v[10:11], v[114:115]
	v_pk_fma_f32 v[0:1], v[16:17], v[70:71], v[38:39] op_sel_hi:[1,0,1]
	v_pk_fma_f32 v[2:3], v[18:19], v[70:71], v[82:83] op_sel_hi:[1,0,1]
	v_pk_fma_f32 v[4:5], v[16:17], v[72:73], v[116:117] op_sel_hi:[1,0,1]
	v_pk_fma_f32 v[6:7], v[18:19], v[72:73], v[114:115] op_sel_hi:[1,0,1]
	v_pk_mul_f32 v[110:111], v[2:3], v[26:27]
	v_pk_mul_f32 v[112:113], v[6:7], v[26:27]
	v_pk_fma_f32 v[110:111], v[0:1], v[24:25], v[110:111]
	v_pk_fma_f32 v[112:113], v[4:5], v[24:25], v[112:113]
	v_add_f32_e32 v110, v110, v111
	v_add_f32_e32 v112, v112, v113
	ds_write_b32 v119, v110 offset:12288
	ds_write_b32 v119, v112 offset:12352
	s_waitcnt lgkmcnt(2)
	v_pk_mul_f32 v[110:111], v[2:3], v[36:37]
	v_pk_mul_f32 v[112:113], v[6:7], v[36:37]
	v_pk_fma_f32 v[110:111], v[0:1], v[34:35], v[110:111]
	v_pk_fma_f32 v[112:113], v[4:5], v[34:35], v[112:113]
	ds_read_b128 v[12:15], v69 offset:37120
	ds_read_b128 v[20:23], v69 offset:37632
	ds_read_b64 v[28:29], v118 offset:38144
	ds_read_b128 v[8:11], v69 offset:36864
	ds_read_b128 v[16:19], v69 offset:37376
	ds_read_b128 v[24:27], v69 offset:37888
	v_add_f32_e32 v70, v110, v111
	v_add_f32_e32 v72, v112, v113
	v_pk_mul_f32 v[38:39], v[78:79], v[108:109] op_sel_hi:[1,0]
	v_add_f32_dpp v70, v70, v70 row_ror:8 row_mask:0xf bank_mask:0xf bound_ctrl:1
	v_add_f32_dpp v72, v72, v72 row_ror:8 row_mask:0xf bank_mask:0xf bound_ctrl:1
	v_pk_mul_f32 v[82:83], v[80:81], v[108:109] op_sel_hi:[1,0]
	v_add_f32_dpp v70, v70, v70 row_ror:4 row_mask:0xf bank_mask:0xf bound_ctrl:1
	v_add_f32_dpp v72, v72, v72 row_ror:4 row_mask:0xf bank_mask:0xf bound_ctrl:1
	v_pk_mul_f32 v[116:117], v[78:79], v[108:109] op_sel:[0,1] op_sel_hi:[1,1]
	v_add_f32_dpp v70, v70, v70 row_ror:2 row_mask:0xf bank_mask:0xf bound_ctrl:1
	v_add_f32_dpp v72, v72, v72 row_ror:2 row_mask:0xf bank_mask:0xf bound_ctrl:1
	v_pk_mul_f32 v[114:115], v[80:81], v[108:109] op_sel:[0,1] op_sel_hi:[1,1]
	v_add_f32_dpp v70, v70, v70 row_ror:1 row_mask:0xf bank_mask:0xf bound_ctrl:1
	v_add_f32_dpp v72, v72, v72 row_ror:1 row_mask:0xf bank_mask:0xf bound_ctrl:1
	v_pk_fma_f32 v[38:39], v[0:1], v[30:31], v[38:39]
	v_pk_fma_f32 v[82:83], v[2:3], v[32:33], v[82:83]
	v_pk_fma_f32 v[116:117], v[4:5], v[30:31], v[116:117]
	v_pk_fma_f32 v[114:115], v[6:7], v[32:33], v[114:115]
	v_pk_fma_f32 v[0:1], v[74:75], v[70:71], v[38:39] op_sel_hi:[1,0,1]
	v_pk_fma_f32 v[2:3], v[76:77], v[70:71], v[82:83] op_sel_hi:[1,0,1]
	v_pk_fma_f32 v[4:5], v[74:75], v[72:73], v[116:117] op_sel_hi:[1,0,1]
	v_pk_fma_f32 v[6:7], v[76:77], v[72:73], v[114:115] op_sel_hi:[1,0,1]
	v_pk_mul_f32 v[110:111], v[2:3], v[106:107]
	v_pk_mul_f32 v[112:113], v[6:7], v[106:107]
	v_pk_fma_f32 v[110:111], v[0:1], v[104:105], v[110:111]
	v_pk_fma_f32 v[112:113], v[4:5], v[104:105], v[112:113]
	v_add_f32_e32 v110, v110, v111
	v_add_f32_e32 v112, v112, v113
	ds_write_b32 v119, v110 offset:14336
	ds_write_b32 v119, v112 offset:14400
	s_waitcnt lgkmcnt(0)
	s_barrier
	v_pk_mul_f32 v[110:111], v[2:3], v[14:15]
	v_pk_mul_f32 v[112:113], v[6:7], v[14:15]
	v_pk_fma_f32 v[110:111], v[0:1], v[12:13], v[110:111]
	v_pk_fma_f32 v[112:113], v[4:5], v[12:13], v[112:113]
	ds_read_b128 v[34:37], v69 offset:38656
	ds_read_b128 v[78:81], v69 offset:39168
	ds_read_b64 v[108:109], v118 offset:39680
	ds_read_b128 v[30:33], v69 offset:38400
	ds_read_b128 v[74:77], v69 offset:38912
	ds_read_b128 v[104:107], v69 offset:39424
	v_add_f32_e32 v70, v110, v111
	v_add_f32_e32 v72, v112, v113
	v_pk_mul_f32 v[38:39], v[20:21], v[28:29] op_sel_hi:[1,0]
	v_add_f32_dpp v70, v70, v70 row_ror:8 row_mask:0xf bank_mask:0xf bound_ctrl:1
	v_add_f32_dpp v72, v72, v72 row_ror:8 row_mask:0xf bank_mask:0xf bound_ctrl:1
	v_pk_mul_f32 v[82:83], v[22:23], v[28:29] op_sel_hi:[1,0]
	v_add_f32_dpp v70, v70, v70 row_ror:4 row_mask:0xf bank_mask:0xf bound_ctrl:1
	v_add_f32_dpp v72, v72, v72 row_ror:4 row_mask:0xf bank_mask:0xf bound_ctrl:1
	v_pk_mul_f32 v[116:117], v[20:21], v[28:29] op_sel:[0,1] op_sel_hi:[1,1]
	v_add_f32_dpp v70, v70, v70 row_ror:2 row_mask:0xf bank_mask:0xf bound_ctrl:1
	v_add_f32_dpp v72, v72, v72 row_ror:2 row_mask:0xf bank_mask:0xf bound_ctrl:1
	v_pk_mul_f32 v[114:115], v[22:23], v[28:29] op_sel:[0,1] op_sel_hi:[1,1]
	v_add_f32_dpp v70, v70, v70 row_ror:1 row_mask:0xf bank_mask:0xf bound_ctrl:1
	v_add_f32_dpp v72, v72, v72 row_ror:1 row_mask:0xf bank_mask:0xf bound_ctrl:1
	v_pk_fma_f32 v[38:39], v[0:1], v[8:9], v[38:39]
	v_pk_fma_f32 v[82:83], v[2:3], v[10:11], v[82:83]
	v_pk_fma_f32 v[116:117], v[4:5], v[8:9], v[116:117]
	v_pk_fma_f32 v[114:115], v[6:7], v[10:11], v[114:115]
	v_pk_fma_f32 v[0:1], v[16:17], v[70:71], v[38:39] op_sel_hi:[1,0,1]
	v_pk_fma_f32 v[2:3], v[18:19], v[70:71], v[82:83] op_sel_hi:[1,0,1]
	v_pk_fma_f32 v[4:5], v[16:17], v[72:73], v[116:117] op_sel_hi:[1,0,1]
	v_pk_fma_f32 v[6:7], v[18:19], v[72:73], v[114:115] op_sel_hi:[1,0,1]
	v_pk_mul_f32 v[110:111], v[2:3], v[26:27]
	v_pk_mul_f32 v[112:113], v[6:7], v[26:27]
	v_pk_fma_f32 v[110:111], v[0:1], v[24:25], v[110:111]
	v_pk_fma_f32 v[112:113], v[4:5], v[24:25], v[112:113]
	v_add_f32_e32 v110, v110, v111
	v_add_f32_e32 v112, v112, v113
	ds_write_b32 v119, v110 offset:16384
	ds_write_b32 v119, v112 offset:16448
	s_waitcnt lgkmcnt(2)
	v_pk_mul_f32 v[110:111], v[2:3], v[36:37]
	v_pk_mul_f32 v[112:113], v[6:7], v[36:37]
	v_pk_fma_f32 v[110:111], v[0:1], v[34:35], v[110:111]
	v_pk_fma_f32 v[112:113], v[4:5], v[34:35], v[112:113]
	ds_read_b128 v[12:15], v69 offset:40192
	ds_read_b128 v[20:23], v69 offset:40704
	ds_read_b64 v[28:29], v118 offset:41216
	ds_read_b128 v[8:11], v69 offset:39936
	ds_read_b128 v[16:19], v69 offset:40448
	ds_read_b128 v[24:27], v69 offset:40960
	v_add_f32_e32 v70, v110, v111
	v_add_f32_e32 v72, v112, v113
	v_pk_mul_f32 v[38:39], v[78:79], v[108:109] op_sel_hi:[1,0]
	v_add_f32_dpp v70, v70, v70 row_ror:8 row_mask:0xf bank_mask:0xf bound_ctrl:1
	v_add_f32_dpp v72, v72, v72 row_ror:8 row_mask:0xf bank_mask:0xf bound_ctrl:1
	v_pk_mul_f32 v[82:83], v[80:81], v[108:109] op_sel_hi:[1,0]
	v_add_f32_dpp v70, v70, v70 row_ror:4 row_mask:0xf bank_mask:0xf bound_ctrl:1
	v_add_f32_dpp v72, v72, v72 row_ror:4 row_mask:0xf bank_mask:0xf bound_ctrl:1
	v_pk_mul_f32 v[116:117], v[78:79], v[108:109] op_sel:[0,1] op_sel_hi:[1,1]
	v_add_f32_dpp v70, v70, v70 row_ror:2 row_mask:0xf bank_mask:0xf bound_ctrl:1
	v_add_f32_dpp v72, v72, v72 row_ror:2 row_mask:0xf bank_mask:0xf bound_ctrl:1
	v_pk_mul_f32 v[114:115], v[80:81], v[108:109] op_sel:[0,1] op_sel_hi:[1,1]
	v_add_f32_dpp v70, v70, v70 row_ror:1 row_mask:0xf bank_mask:0xf bound_ctrl:1
	v_add_f32_dpp v72, v72, v72 row_ror:1 row_mask:0xf bank_mask:0xf bound_ctrl:1
	v_pk_fma_f32 v[38:39], v[0:1], v[30:31], v[38:39]
	v_pk_fma_f32 v[82:83], v[2:3], v[32:33], v[82:83]
	v_pk_fma_f32 v[116:117], v[4:5], v[30:31], v[116:117]
	v_pk_fma_f32 v[114:115], v[6:7], v[32:33], v[114:115]
	v_pk_fma_f32 v[0:1], v[74:75], v[70:71], v[38:39] op_sel_hi:[1,0,1]
	v_pk_fma_f32 v[2:3], v[76:77], v[70:71], v[82:83] op_sel_hi:[1,0,1]
	v_pk_fma_f32 v[4:5], v[74:75], v[72:73], v[116:117] op_sel_hi:[1,0,1]
	v_pk_fma_f32 v[6:7], v[76:77], v[72:73], v[114:115] op_sel_hi:[1,0,1]
	v_pk_mul_f32 v[110:111], v[2:3], v[106:107]
	v_pk_mul_f32 v[112:113], v[6:7], v[106:107]
	v_pk_fma_f32 v[110:111], v[0:1], v[104:105], v[110:111]
	v_pk_fma_f32 v[112:113], v[4:5], v[104:105], v[112:113]
	v_add_f32_e32 v110, v110, v111
	v_add_f32_e32 v112, v112, v113
	ds_write_b32 v119, v110 offset:18432
	ds_write_b32 v119, v112 offset:18496
	s_waitcnt lgkmcnt(2)
	v_pk_mul_f32 v[110:111], v[2:3], v[14:15]
	v_pk_mul_f32 v[112:113], v[6:7], v[14:15]
	v_pk_fma_f32 v[110:111], v[0:1], v[12:13], v[110:111]
	v_pk_fma_f32 v[112:113], v[4:5], v[12:13], v[112:113]
	ds_read_b128 v[34:37], v69 offset:41728
	ds_read_b128 v[78:81], v69 offset:42240
	ds_read_b64 v[108:109], v118 offset:42752
	ds_read_b128 v[30:33], v69 offset:41472
	ds_read_b128 v[74:77], v69 offset:41984
	ds_read_b128 v[104:107], v69 offset:42496
	v_add_f32_e32 v70, v110, v111
	v_add_f32_e32 v72, v112, v113
	v_pk_mul_f32 v[38:39], v[20:21], v[28:29] op_sel_hi:[1,0]
	v_add_f32_dpp v70, v70, v70 row_ror:8 row_mask:0xf bank_mask:0xf bound_ctrl:1
	v_add_f32_dpp v72, v72, v72 row_ror:8 row_mask:0xf bank_mask:0xf bound_ctrl:1
	v_pk_mul_f32 v[82:83], v[22:23], v[28:29] op_sel_hi:[1,0]
	v_add_f32_dpp v70, v70, v70 row_ror:4 row_mask:0xf bank_mask:0xf bound_ctrl:1
	v_add_f32_dpp v72, v72, v72 row_ror:4 row_mask:0xf bank_mask:0xf bound_ctrl:1
	v_pk_mul_f32 v[116:117], v[20:21], v[28:29] op_sel:[0,1] op_sel_hi:[1,1]
	v_add_f32_dpp v70, v70, v70 row_ror:2 row_mask:0xf bank_mask:0xf bound_ctrl:1
	v_add_f32_dpp v72, v72, v72 row_ror:2 row_mask:0xf bank_mask:0xf bound_ctrl:1
	v_pk_mul_f32 v[114:115], v[22:23], v[28:29] op_sel:[0,1] op_sel_hi:[1,1]
	v_add_f32_dpp v70, v70, v70 row_ror:1 row_mask:0xf bank_mask:0xf bound_ctrl:1
	v_add_f32_dpp v72, v72, v72 row_ror:1 row_mask:0xf bank_mask:0xf bound_ctrl:1
	v_pk_fma_f32 v[38:39], v[0:1], v[8:9], v[38:39]
	v_pk_fma_f32 v[82:83], v[2:3], v[10:11], v[82:83]
	v_pk_fma_f32 v[116:117], v[4:5], v[8:9], v[116:117]
	v_pk_fma_f32 v[114:115], v[6:7], v[10:11], v[114:115]
	v_pk_fma_f32 v[0:1], v[16:17], v[70:71], v[38:39] op_sel_hi:[1,0,1]
	v_pk_fma_f32 v[2:3], v[18:19], v[70:71], v[82:83] op_sel_hi:[1,0,1]
	v_pk_fma_f32 v[4:5], v[16:17], v[72:73], v[116:117] op_sel_hi:[1,0,1]
	v_pk_fma_f32 v[6:7], v[18:19], v[72:73], v[114:115] op_sel_hi:[1,0,1]
	v_pk_mul_f32 v[110:111], v[2:3], v[26:27]
	v_pk_mul_f32 v[112:113], v[6:7], v[26:27]
	v_pk_fma_f32 v[110:111], v[0:1], v[24:25], v[110:111]
	v_pk_fma_f32 v[112:113], v[4:5], v[24:25], v[112:113]
	v_add_f32_e32 v110, v110, v111
	v_add_f32_e32 v112, v112, v113
	ds_write_b32 v119, v110 offset:20480
	ds_write_b32 v119, v112 offset:20544
	s_waitcnt lgkmcnt(2)
	v_pk_mul_f32 v[110:111], v[2:3], v[36:37]
	v_pk_mul_f32 v[112:113], v[6:7], v[36:37]
	v_pk_fma_f32 v[110:111], v[0:1], v[34:35], v[110:111]
	v_pk_fma_f32 v[112:113], v[4:5], v[34:35], v[112:113]
	ds_read_b128 v[12:15], v69 offset:43264
	ds_read_b128 v[20:23], v69 offset:43776
	ds_read_b64 v[28:29], v118 offset:44288
	ds_read_b128 v[8:11], v69 offset:43008
	ds_read_b128 v[16:19], v69 offset:43520
	ds_read_b128 v[24:27], v69 offset:44032
	v_add_f32_e32 v70, v110, v111
	v_add_f32_e32 v72, v112, v113
	v_pk_mul_f32 v[38:39], v[78:79], v[108:109] op_sel_hi:[1,0]
	v_add_f32_dpp v70, v70, v70 row_ror:8 row_mask:0xf bank_mask:0xf bound_ctrl:1
	v_add_f32_dpp v72, v72, v72 row_ror:8 row_mask:0xf bank_mask:0xf bound_ctrl:1
	v_pk_mul_f32 v[82:83], v[80:81], v[108:109] op_sel_hi:[1,0]
	v_add_f32_dpp v70, v70, v70 row_ror:4 row_mask:0xf bank_mask:0xf bound_ctrl:1
	v_add_f32_dpp v72, v72, v72 row_ror:4 row_mask:0xf bank_mask:0xf bound_ctrl:1
	v_pk_mul_f32 v[116:117], v[78:79], v[108:109] op_sel:[0,1] op_sel_hi:[1,1]
	v_add_f32_dpp v70, v70, v70 row_ror:2 row_mask:0xf bank_mask:0xf bound_ctrl:1
	v_add_f32_dpp v72, v72, v72 row_ror:2 row_mask:0xf bank_mask:0xf bound_ctrl:1
	v_pk_mul_f32 v[114:115], v[80:81], v[108:109] op_sel:[0,1] op_sel_hi:[1,1]
	v_add_f32_dpp v70, v70, v70 row_ror:1 row_mask:0xf bank_mask:0xf bound_ctrl:1
	v_add_f32_dpp v72, v72, v72 row_ror:1 row_mask:0xf bank_mask:0xf bound_ctrl:1
	v_pk_fma_f32 v[38:39], v[0:1], v[30:31], v[38:39]
	v_pk_fma_f32 v[82:83], v[2:3], v[32:33], v[82:83]
	v_pk_fma_f32 v[116:117], v[4:5], v[30:31], v[116:117]
	v_pk_fma_f32 v[114:115], v[6:7], v[32:33], v[114:115]
	v_pk_fma_f32 v[0:1], v[74:75], v[70:71], v[38:39] op_sel_hi:[1,0,1]
	v_pk_fma_f32 v[2:3], v[76:77], v[70:71], v[82:83] op_sel_hi:[1,0,1]
	v_pk_fma_f32 v[4:5], v[74:75], v[72:73], v[116:117] op_sel_hi:[1,0,1]
	v_pk_fma_f32 v[6:7], v[76:77], v[72:73], v[114:115] op_sel_hi:[1,0,1]
	v_pk_mul_f32 v[110:111], v[2:3], v[106:107]
	v_pk_mul_f32 v[112:113], v[6:7], v[106:107]
	v_pk_fma_f32 v[110:111], v[0:1], v[104:105], v[110:111]
	v_pk_fma_f32 v[112:113], v[4:5], v[104:105], v[112:113]
	v_add_f32_e32 v110, v110, v111
	v_add_f32_e32 v112, v112, v113
	ds_write_b32 v119, v110 offset:22528
	ds_write_b32 v119, v112 offset:22592
	s_waitcnt lgkmcnt(2)
	v_pk_mul_f32 v[110:111], v[2:3], v[14:15]
	v_pk_mul_f32 v[112:113], v[6:7], v[14:15]
	v_pk_fma_f32 v[110:111], v[0:1], v[12:13], v[110:111]
	v_pk_fma_f32 v[112:113], v[4:5], v[12:13], v[112:113]
	ds_read_b128 v[34:37], v69 offset:44800
	ds_read_b128 v[78:81], v69 offset:45312
	ds_read_b64 v[108:109], v118 offset:45824
	ds_read_b128 v[30:33], v69 offset:44544
	ds_read_b128 v[74:77], v69 offset:45056
	ds_read_b128 v[104:107], v69 offset:45568
	v_add_f32_e32 v70, v110, v111
	v_add_f32_e32 v72, v112, v113
	v_pk_mul_f32 v[38:39], v[20:21], v[28:29] op_sel_hi:[1,0]
	v_add_f32_dpp v70, v70, v70 row_ror:8 row_mask:0xf bank_mask:0xf bound_ctrl:1
	v_add_f32_dpp v72, v72, v72 row_ror:8 row_mask:0xf bank_mask:0xf bound_ctrl:1
	v_pk_mul_f32 v[82:83], v[22:23], v[28:29] op_sel_hi:[1,0]
	v_add_f32_dpp v70, v70, v70 row_ror:4 row_mask:0xf bank_mask:0xf bound_ctrl:1
	v_add_f32_dpp v72, v72, v72 row_ror:4 row_mask:0xf bank_mask:0xf bound_ctrl:1
	v_pk_mul_f32 v[116:117], v[20:21], v[28:29] op_sel:[0,1] op_sel_hi:[1,1]
	v_add_f32_dpp v70, v70, v70 row_ror:2 row_mask:0xf bank_mask:0xf bound_ctrl:1
	v_add_f32_dpp v72, v72, v72 row_ror:2 row_mask:0xf bank_mask:0xf bound_ctrl:1
	v_pk_mul_f32 v[114:115], v[22:23], v[28:29] op_sel:[0,1] op_sel_hi:[1,1]
	v_add_f32_dpp v70, v70, v70 row_ror:1 row_mask:0xf bank_mask:0xf bound_ctrl:1
	v_add_f32_dpp v72, v72, v72 row_ror:1 row_mask:0xf bank_mask:0xf bound_ctrl:1
	v_pk_fma_f32 v[38:39], v[0:1], v[8:9], v[38:39]
	v_pk_fma_f32 v[82:83], v[2:3], v[10:11], v[82:83]
	v_pk_fma_f32 v[116:117], v[4:5], v[8:9], v[116:117]
	v_pk_fma_f32 v[114:115], v[6:7], v[10:11], v[114:115]
	v_pk_fma_f32 v[0:1], v[16:17], v[70:71], v[38:39] op_sel_hi:[1,0,1]
	v_pk_fma_f32 v[2:3], v[18:19], v[70:71], v[82:83] op_sel_hi:[1,0,1]
	v_pk_fma_f32 v[4:5], v[16:17], v[72:73], v[116:117] op_sel_hi:[1,0,1]
	v_pk_fma_f32 v[6:7], v[18:19], v[72:73], v[114:115] op_sel_hi:[1,0,1]
	v_pk_mul_f32 v[110:111], v[2:3], v[26:27]
	v_pk_mul_f32 v[112:113], v[6:7], v[26:27]
	v_pk_fma_f32 v[110:111], v[0:1], v[24:25], v[110:111]
	v_pk_fma_f32 v[112:113], v[4:5], v[24:25], v[112:113]
	v_add_f32_e32 v110, v110, v111
	v_add_f32_e32 v112, v112, v113
	ds_write_b32 v119, v110 offset:24576
	ds_write_b32 v119, v112 offset:24640
	s_waitcnt lgkmcnt(2)
	v_pk_mul_f32 v[110:111], v[2:3], v[36:37]
	v_pk_mul_f32 v[112:113], v[6:7], v[36:37]
	v_pk_fma_f32 v[110:111], v[0:1], v[34:35], v[110:111]
	v_pk_fma_f32 v[112:113], v[4:5], v[34:35], v[112:113]
	ds_read_b128 v[12:15], v69 offset:46336
	ds_read_b128 v[20:23], v69 offset:46848
	ds_read_b64 v[28:29], v118 offset:47360
	ds_read_b128 v[8:11], v69 offset:46080
	ds_read_b128 v[16:19], v69 offset:46592
	ds_read_b128 v[24:27], v69 offset:47104
	v_add_f32_e32 v70, v110, v111
	v_add_f32_e32 v72, v112, v113
	v_pk_mul_f32 v[38:39], v[78:79], v[108:109] op_sel_hi:[1,0]
	v_add_f32_dpp v70, v70, v70 row_ror:8 row_mask:0xf bank_mask:0xf bound_ctrl:1
	v_add_f32_dpp v72, v72, v72 row_ror:8 row_mask:0xf bank_mask:0xf bound_ctrl:1
	v_pk_mul_f32 v[82:83], v[80:81], v[108:109] op_sel_hi:[1,0]
	v_add_f32_dpp v70, v70, v70 row_ror:4 row_mask:0xf bank_mask:0xf bound_ctrl:1
	v_add_f32_dpp v72, v72, v72 row_ror:4 row_mask:0xf bank_mask:0xf bound_ctrl:1
	v_pk_mul_f32 v[116:117], v[78:79], v[108:109] op_sel:[0,1] op_sel_hi:[1,1]
	v_add_f32_dpp v70, v70, v70 row_ror:2 row_mask:0xf bank_mask:0xf bound_ctrl:1
	v_add_f32_dpp v72, v72, v72 row_ror:2 row_mask:0xf bank_mask:0xf bound_ctrl:1
	v_pk_mul_f32 v[114:115], v[80:81], v[108:109] op_sel:[0,1] op_sel_hi:[1,1]
	v_add_f32_dpp v70, v70, v70 row_ror:1 row_mask:0xf bank_mask:0xf bound_ctrl:1
	v_add_f32_dpp v72, v72, v72 row_ror:1 row_mask:0xf bank_mask:0xf bound_ctrl:1
	v_pk_fma_f32 v[38:39], v[0:1], v[30:31], v[38:39]
	v_pk_fma_f32 v[82:83], v[2:3], v[32:33], v[82:83]
	v_pk_fma_f32 v[116:117], v[4:5], v[30:31], v[116:117]
	v_pk_fma_f32 v[114:115], v[6:7], v[32:33], v[114:115]
	v_pk_fma_f32 v[0:1], v[74:75], v[70:71], v[38:39] op_sel_hi:[1,0,1]
	v_pk_fma_f32 v[2:3], v[76:77], v[70:71], v[82:83] op_sel_hi:[1,0,1]
	v_pk_fma_f32 v[4:5], v[74:75], v[72:73], v[116:117] op_sel_hi:[1,0,1]
	v_pk_fma_f32 v[6:7], v[76:77], v[72:73], v[114:115] op_sel_hi:[1,0,1]
	v_pk_mul_f32 v[110:111], v[2:3], v[106:107]
	v_pk_mul_f32 v[112:113], v[6:7], v[106:107]
	v_pk_fma_f32 v[110:111], v[0:1], v[104:105], v[110:111]
	v_pk_fma_f32 v[112:113], v[4:5], v[104:105], v[112:113]
	v_add_f32_e32 v110, v110, v111
	v_add_f32_e32 v112, v112, v113
	ds_write_b32 v119, v110 offset:26624
	ds_write_b32 v119, v112 offset:26688
	s_waitcnt lgkmcnt(2)
	v_pk_mul_f32 v[110:111], v[2:3], v[14:15]
	v_pk_mul_f32 v[112:113], v[6:7], v[14:15]
	v_pk_fma_f32 v[110:111], v[0:1], v[12:13], v[110:111]
	v_pk_fma_f32 v[112:113], v[4:5], v[12:13], v[112:113]
	ds_read_b128 v[34:37], v69 offset:47872
	ds_read_b128 v[78:81], v69 offset:48384
	ds_read_b64 v[108:109], v118 offset:48896
	ds_read_b128 v[30:33], v69 offset:47616
	ds_read_b128 v[74:77], v69 offset:48128
	ds_read_b128 v[104:107], v69 offset:48640
	v_add_f32_e32 v70, v110, v111
	v_add_f32_e32 v72, v112, v113
	v_pk_mul_f32 v[38:39], v[20:21], v[28:29] op_sel_hi:[1,0]
	v_add_f32_dpp v70, v70, v70 row_ror:8 row_mask:0xf bank_mask:0xf bound_ctrl:1
	v_add_f32_dpp v72, v72, v72 row_ror:8 row_mask:0xf bank_mask:0xf bound_ctrl:1
	v_pk_mul_f32 v[82:83], v[22:23], v[28:29] op_sel_hi:[1,0]
	v_add_f32_dpp v70, v70, v70 row_ror:4 row_mask:0xf bank_mask:0xf bound_ctrl:1
	v_add_f32_dpp v72, v72, v72 row_ror:4 row_mask:0xf bank_mask:0xf bound_ctrl:1
	v_pk_mul_f32 v[116:117], v[20:21], v[28:29] op_sel:[0,1] op_sel_hi:[1,1]
	v_add_f32_dpp v70, v70, v70 row_ror:2 row_mask:0xf bank_mask:0xf bound_ctrl:1
	v_add_f32_dpp v72, v72, v72 row_ror:2 row_mask:0xf bank_mask:0xf bound_ctrl:1
	v_pk_mul_f32 v[114:115], v[22:23], v[28:29] op_sel:[0,1] op_sel_hi:[1,1]
	v_add_f32_dpp v70, v70, v70 row_ror:1 row_mask:0xf bank_mask:0xf bound_ctrl:1
	v_add_f32_dpp v72, v72, v72 row_ror:1 row_mask:0xf bank_mask:0xf bound_ctrl:1
	v_pk_fma_f32 v[38:39], v[0:1], v[8:9], v[38:39]
	v_pk_fma_f32 v[82:83], v[2:3], v[10:11], v[82:83]
	v_pk_fma_f32 v[116:117], v[4:5], v[8:9], v[116:117]
	v_pk_fma_f32 v[114:115], v[6:7], v[10:11], v[114:115]
	v_pk_fma_f32 v[0:1], v[16:17], v[70:71], v[38:39] op_sel_hi:[1,0,1]
	v_pk_fma_f32 v[2:3], v[18:19], v[70:71], v[82:83] op_sel_hi:[1,0,1]
	v_pk_fma_f32 v[4:5], v[16:17], v[72:73], v[116:117] op_sel_hi:[1,0,1]
	v_pk_fma_f32 v[6:7], v[18:19], v[72:73], v[114:115] op_sel_hi:[1,0,1]
	v_pk_mul_f32 v[110:111], v[2:3], v[26:27]
	v_pk_mul_f32 v[112:113], v[6:7], v[26:27]
	v_pk_fma_f32 v[110:111], v[0:1], v[24:25], v[110:111]
	v_pk_fma_f32 v[112:113], v[4:5], v[24:25], v[112:113]
	v_add_f32_e32 v110, v110, v111
	v_add_f32_e32 v112, v112, v113
	ds_write_b32 v119, v110 offset:28672
	ds_write_b32 v119, v112 offset:28736
	s_waitcnt lgkmcnt(2)
	v_pk_mul_f32 v[110:111], v[2:3], v[36:37]
	v_pk_mul_f32 v[112:113], v[6:7], v[36:37]
	v_pk_fma_f32 v[110:111], v[0:1], v[34:35], v[110:111]
	v_pk_fma_f32 v[112:113], v[4:5], v[34:35], v[112:113]
	v_add_f32_e32 v70, v110, v111
	v_add_f32_e32 v72, v112, v113
	v_pk_mul_f32 v[38:39], v[78:79], v[108:109] op_sel_hi:[1,0]
	v_add_f32_dpp v70, v70, v70 row_ror:8 row_mask:0xf bank_mask:0xf bound_ctrl:1
	v_add_f32_dpp v72, v72, v72 row_ror:8 row_mask:0xf bank_mask:0xf bound_ctrl:1
	v_pk_mul_f32 v[82:83], v[80:81], v[108:109] op_sel_hi:[1,0]
	v_add_f32_dpp v70, v70, v70 row_ror:4 row_mask:0xf bank_mask:0xf bound_ctrl:1
	v_add_f32_dpp v72, v72, v72 row_ror:4 row_mask:0xf bank_mask:0xf bound_ctrl:1
	v_pk_mul_f32 v[116:117], v[78:79], v[108:109] op_sel:[0,1] op_sel_hi:[1,1]
	v_add_f32_dpp v70, v70, v70 row_ror:2 row_mask:0xf bank_mask:0xf bound_ctrl:1
	v_add_f32_dpp v72, v72, v72 row_ror:2 row_mask:0xf bank_mask:0xf bound_ctrl:1
	v_pk_mul_f32 v[114:115], v[80:81], v[108:109] op_sel:[0,1] op_sel_hi:[1,1]
	v_add_f32_dpp v70, v70, v70 row_ror:1 row_mask:0xf bank_mask:0xf bound_ctrl:1
	v_add_f32_dpp v72, v72, v72 row_ror:1 row_mask:0xf bank_mask:0xf bound_ctrl:1
	v_pk_fma_f32 v[38:39], v[0:1], v[30:31], v[38:39]
	v_pk_fma_f32 v[82:83], v[2:3], v[32:33], v[82:83]
	v_pk_fma_f32 v[116:117], v[4:5], v[30:31], v[116:117]
	v_pk_fma_f32 v[114:115], v[6:7], v[32:33], v[114:115]
	v_pk_fma_f32 v[0:1], v[74:75], v[70:71], v[38:39] op_sel_hi:[1,0,1]
	v_pk_fma_f32 v[2:3], v[76:77], v[70:71], v[82:83] op_sel_hi:[1,0,1]
	v_pk_fma_f32 v[4:5], v[74:75], v[72:73], v[116:117] op_sel_hi:[1,0,1]
	v_pk_fma_f32 v[6:7], v[76:77], v[72:73], v[114:115] op_sel_hi:[1,0,1]
	v_pk_mul_f32 v[110:111], v[2:3], v[106:107]
	v_pk_mul_f32 v[112:113], v[6:7], v[106:107]
	v_pk_fma_f32 v[110:111], v[0:1], v[104:105], v[110:111]
	v_pk_fma_f32 v[112:113], v[4:5], v[104:105], v[112:113]
	v_add_f32_e32 v110, v110, v111
	v_add_f32_e32 v112, v112, v113
	ds_write_b32 v119, v110 offset:30720
	ds_write_b32 v119, v112 offset:30784
	s_waitcnt lgkmcnt(0)
	s_barrier
	s_setprio 0
	s_branch .Lsc_next
.Lsc_helper:
	s_cmp_eq_u32 s25, 0
	s_cbranch_scc1 .Lsc_h0
	ds_read_b128 v[120:123], v145 offset:16384
	ds_read_b128 v[124:127], v145 offset:16400
	ds_read_b128 v[128:131], v145 offset:16416
	ds_read_b128 v[132:135], v145 offset:16432
	s_add_i32 s10, s26, -16
	s_ashr_i32 s11, s10, 31
	v_lshl_add_u64 v[136:137], v[64:65], 0, s[10:11]
	v_mad_u64_u32 v[138:139], s[12:13], v136, s74, v[66:67]
	v_mad_i32_i24 v139, v137, s74, v139
	s_waitcnt lgkmcnt(0)
	v_add_f32_e32 v120, v120, v121
	v_add_f32_e32 v122, v122, v123
	v_add_f32_e32 v124, v124, v125
	v_add_f32_e32 v126, v126, v127
	v_add_f32_e32 v128, v128, v129
	v_add_f32_e32 v130, v130, v131
	v_add_f32_e32 v132, v132, v133
	v_add_f32_e32 v134, v134, v135
	v_add_f32_e32 v120, v120, v122
	v_add_f32_e32 v124, v124, v126
	v_add_f32_e32 v128, v128, v130
	v_add_f32_e32 v132, v132, v134
	v_add_f32_e32 v120, v120, v124
	v_add_f32_e32 v128, v128, v132
	v_add_f32_e32 v120, v120, v128
	v_cvt_pk_bf16_f32 v140, v120, v149
	global_store_short v[138:139], v140, off
.Lsc_h0:
	s_cmpk_eq_i32 s25, 0x7f
	s_cbranch_scc1 .Lsc_h0s
	v_ashrrev_i32_e32 v69, 31, v68
	v_lshl_add_u64 v[8:9], s[38:39], 0, v[68:69]
	v_cmp_lt_i32_e32 vcc, 0, v68
	v_mad_u64_u32 v[10:11], s[12:13], v8, s75, v[60:61]
	v_mad_i32_i24 v11, v9, s75, v11
	v_cndmask_b32_e64 v35, 0, -1, vcc
	v_cndmask_b32_e32 v34, 0, v178, vcc
	v_lshl_add_u64 v[12:13], v[10:11], 0, v[34:35]
	global_load_dwordx2 v[36:37], v[10:11], off
	global_load_dwordx2 v[38:39], v[10:11], off offset:1536
	global_load_dwordx2 v[72:73], v[10:11], off offset:3072
	global_load_dwordx2 v[74:75], v[12:13], off
	global_load_dwordx2 v[76:77], v[12:13], off offset:1536
	global_load_dwordx2 v[78:79], v[12:13], off offset:3072
	v_mad_u64_u32 v[10:11], s[12:13], v8, s89, v[62:63]
	v_mad_i32_i24 v11, v9, s89, v11
	global_load_dwordx2 v[22:23], v[10:11], off
	global_load_dwordx2 v[24:25], v[10:11], off offset:1536
	ds_read_b128 v[16:19], v84
	ds_read_b128 v[26:29], v85
	ds_read_b128 v[12:15], v86
	ds_read_b128 v[30:33], v87
	ds_read_b128 v[8:11], v88
.Lsc_h0s:
	s_waitcnt lgkmcnt(0)
	s_barrier
	ds_read_b128 v[120:123], v145 offset:0
	ds_read_b128 v[124:127], v145 offset:16
	ds_read_b128 v[128:131], v145 offset:32
	ds_read_b128 v[132:135], v145 offset:48
	s_add_i32 s10, s26, -8
	s_ashr_i32 s11, s10, 31
	v_lshl_add_u64 v[136:137], v[64:65], 0, s[10:11]
	v_mad_u64_u32 v[138:139], s[12:13], v136, s74, v[66:67]
	v_mad_i32_i24 v139, v137, s74, v139
	s_waitcnt lgkmcnt(0)
	v_add_f32_e32 v120, v120, v121
	v_add_f32_e32 v122, v122, v123
	v_add_f32_e32 v124, v124, v125
	v_add_f32_e32 v126, v126, v127
	v_add_f32_e32 v128, v128, v129
	v_add_f32_e32 v130, v130, v131
	v_add_f32_e32 v132, v132, v133
	v_add_f32_e32 v134, v134, v135
	v_add_f32_e32 v120, v120, v122
	v_add_f32_e32 v124, v124, v126
	v_add_f32_e32 v128, v128, v130
	v_add_f32_e32 v132, v132, v134
	v_add_f32_e32 v120, v120, v124
	v_add_f32_e32 v128, v128, v132
	v_add_f32_e32 v120, v120, v128
	v_cvt_pk_bf16_f32 v140, v120, v149
	global_store_short v[138:139], v140, off
	s_cmpk_eq_i32 s25, 0x7f
	s_cbranch_scc1 .Lsc_h1s
	s_waitcnt vmcnt(5)
	v_lshlrev_b32_e32 v80, 16, v72
	v_and_b32_e32 v81, 0xffff0000, v72
	v_lshlrev_b32_e32 v72, 16, v73
	s_waitcnt vmcnt(2)
	v_and_b32_e32 v69, v78, v35
	v_and_b32_e32 v34, v79, v35
	v_lshlrev_b32_e32 v78, 16, v69
	v_and_b32_e32 v79, 0xffff0000, v69
	v_pk_add_f32 v[78:79], v[78:79], v[80:81] neg_lo:[0,1] neg_hi:[0,1]
	v_and_b32_e32 v73, 0xffff0000, v73
	s_waitcnt lgkmcnt(2)
	v_pk_fma_f32 v[12:13], v[78:79], v[12:13], v[80:81]
	v_lshlrev_b32_e32 v78, 16, v34
	v_and_b32_e32 v79, 0xffff0000, v34
	v_pk_add_f32 v[78:79], v[78:79], v[72:73] neg_lo:[0,1] neg_hi:[0,1]
	v_and_b32_e32 v69, v77, v35
	v_and_b32_e32 v70, v76, v35
	v_and_b32_e32 v75, v75, v35
	v_and_b32_e32 v35, v74, v35
	v_pk_fma_f32 v[14:15], v[78:79], v[14:15], v[72:73]
	v_lshlrev_b32_e32 v34, 16, v35
	v_and_b32_e32 v35, 0xffff0000, v35
	v_lshlrev_b32_e32 v72, 16, v36
	v_and_b32_e32 v73, 0xffff0000, v36
	v_pk_add_f32 v[34:35], v[34:35], v[72:73] neg_lo:[0,1] neg_hi:[0,1]
	v_lshlrev_b32_e32 v36, 16, v37
	v_pk_fma_f32 v[16:17], v[34:35], v[16:17], v[72:73]
	v_lshlrev_b32_e32 v34, 16, v75
	v_and_b32_e32 v35, 0xffff0000, v75
	v_and_b32_e32 v37, 0xffff0000, v37
	v_pk_add_f32 v[34:35], v[34:35], v[36:37] neg_lo:[0,1] neg_hi:[0,1]
	s_waitcnt vmcnt(1)
	v_lshlrev_b32_e32 v20, 16, v22
	v_pk_fma_f32 v[18:19], v[34:35], v[18:19], v[36:37]
	v_lshlrev_b32_e32 v34, 16, v70
	v_and_b32_e32 v35, 0xffff0000, v70
	v_lshlrev_b32_e32 v36, 16, v38
	v_and_b32_e32 v37, 0xffff0000, v38
	v_pk_add_f32 v[34:35], v[34:35], v[36:37] neg_lo:[0,1] neg_hi:[0,1]
	v_lshlrev_b32_e32 v38, 16, v39
	v_pk_fma_f32 v[26:27], v[34:35], v[26:27], v[36:37]
	v_lshlrev_b32_e32 v36, 16, v69
	v_and_b32_e32 v37, 0xffff0000, v69
	v_and_b32_e32 v39, 0xffff0000, v39
	v_pk_add_f32 v[36:37], v[36:37], v[38:39] neg_lo:[0,1] neg_hi:[0,1]
	s_waitcnt lgkmcnt(1)
	v_pk_mul_f32 v[30:31], v[30:31], v[26:27]
	v_pk_fma_f32 v[28:29], v[36:37], v[28:29], v[38:39]
	v_pk_mul_f32 v[34:35], v[30:31], v[30:31]
	v_pk_mul_f32 v[32:33], v[32:33], v[28:29]
	v_add_f32_e32 v34, v34, v35
	v_pk_mul_f32 v[36:37], v[32:33], v[32:33]
	v_and_b32_e32 v21, 0xffff0000, v22
	v_add_f32_e32 v34, v36, v34
	v_add_f32_e32 v34, v37, v34
	v_lshlrev_b32_e32 v22, 16, v23
	v_and_b32_e32 v23, 0xffff0000, v23
	v_add_f32_dpp v34, v34, v34 row_ror:8 row_mask:0xf bank_mask:0xf bound_ctrl:1
	v_mul_f32_e32 v20, 0x3fb8aa3b, v20
	v_mul_f32_e32 v21, 0x3fb8aa3b, v21
	v_add_f32_dpp v34, v34, v34 row_ror:4 row_mask:0xf bank_mask:0xf bound_ctrl:1
	v_mul_f32_e32 v22, 0x3fb8aa3b, v22
	v_mul_f32_e32 v23, 0x3fb8aa3b, v23
	v_add_f32_dpp v34, v34, v34 row_ror:2 row_mask:0xf bank_mask:0xf bound_ctrl:1
	v_exp_f32_e32 v20, v20
	v_exp_f32_e32 v21, v21
	v_add_f32_dpp v34, v34, v34 row_ror:1 row_mask:0xf bank_mask:0xf bound_ctrl:1
	v_cmp_gt_f32_e32 vcc, s95, v34
	v_mul_f32_e32 v35, 0x4f800000, v34
	v_exp_f32_e32 v22, v22
	v_cndmask_b32_e32 v34, v34, v35, vcc
	v_sqrt_f32_e32 v35, v34
	v_exp_f32_e32 v23, v23
	v_add_u32_e32 v36, -1, v35
	v_fma_f32 v37, -v36, v35, v34
	v_cmp_ge_f32_e64 s[12:13], 0, v37
	v_add_u32_e32 v37, 1, v35
	s_nop 0
	v_cndmask_b32_e64 v36, v35, v36, s[12:13]
	v_fma_f32 v35, -v37, v35, v34
	v_cmp_lt_f32_e64 s[12:13], 0, v35
	s_nop 1
	v_cndmask_b32_e64 v35, v36, v37, s[12:13]
	v_mul_f32_e32 v36, 0x37800000, v35
	v_cndmask_b32_e32 v35, v35, v36, vcc
	v_cmp_class_f32_e32 vcc, v34, v170
	s_nop 1
	v_cndmask_b32_e32 v34, v35, v34, vcc
	v_max_f32_e32 v34, 0x2b8cbccc, v34
	v_div_scale_f32 v35, s[12:13], v34, v34, 1.0
	v_rcp_f32_e32 v36, v35
	s_nop 0
	v_fma_f32 v37, -v35, v36, 1.0
	v_fmac_f32_e32 v36, v37, v36
	v_div_scale_f32 v37, vcc, 1.0, v34, 1.0
	v_mul_f32_e32 v38, v37, v36
	v_fma_f32 v39, -v35, v38, v37
	v_fmac_f32_e32 v38, v39, v36
	v_fma_f32 v35, -v35, v38, v37
	v_div_fmas_f32 v35, v35, v36, v38
	v_div_fixup_f32 v34, v35, v34, 1.0
	v_add_u32_e32 v35, s44, v93
	ds_write_b128 v35, v[20:23]
	v_pk_mul_f32 v[22:23], v[32:33], v[34:35] op_sel_hi:[1,0] neg_lo:[0,1] neg_hi:[0,1]
	v_pk_mul_f32 v[20:21], v[30:31], v[34:35] op_sel_hi:[1,0] neg_lo:[0,1] neg_hi:[0,1]
	ds_write_b128 v35, v[20:23] offset:256
	v_pk_mul_f32 v[20:21], v[30:31], v[34:35] op_sel_hi:[1,0]
	v_pk_mul_f32 v[22:23], v[32:33], v[34:35] op_sel_hi:[1,0]
	s_waitcnt vmcnt(0)
	v_lshlrev_b32_e32 v30, 16, v24
	v_and_b32_e32 v31, 0xffff0000, v24
	v_lshlrev_b32_e32 v24, 16, v25
	v_and_b32_e32 v25, 0xffff0000, v25
	v_pk_mul_f32 v[22:23], v[22:23], v[24:25]
	v_pk_mul_f32 v[20:21], v[20:21], v[30:31]
	ds_write_b128 v35, v[20:23] offset:512
	v_pk_add_f32 v[20:21], v[24:25], -1.0 op_sel_hi:[1,0]
	v_pk_add_f32 v[22:23], v[30:31], -1.0 op_sel_hi:[1,0]
	s_waitcnt lgkmcnt(3)
	v_pk_fma_f32 v[10:11], v[20:21], v[10:11], 1.0 op_sel_hi:[1,1,0]
	v_pk_fma_f32 v[8:9], v[22:23], v[8:9], 1.0 op_sel_hi:[1,1,0]
	v_pk_mul_f32 v[10:11], v[28:29], v[10:11]
	v_pk_mul_f32 v[8:9], v[26:27], v[8:9]
	ds_write_b128 v35, v[8:11] offset:768
	ds_write_b128 v35, v[16:19] offset:1024
	ds_write_b128 v35, v[12:15] offset:1280
.Lsc_h1s:
	s_waitcnt lgkmcnt(0)
	s_barrier
	ds_read_b128 v[120:123], v145 offset:16384
	ds_read_b128 v[124:127], v145 offset:16400
	ds_read_b128 v[128:131], v145 offset:16416
	ds_read_b128 v[132:135], v145 offset:16432
	s_add_i32 s10, s26, 0
	s_ashr_i32 s11, s10, 31
	v_lshl_add_u64 v[136:137], v[64:65], 0, s[10:11]
	v_mad_u64_u32 v[138:139], s[12:13], v136, s74, v[66:67]
	v_mad_i32_i24 v139, v137, s74, v139
	s_waitcnt lgkmcnt(0)
	v_add_f32_e32 v120, v120, v121
	v_add_f32_e32 v122, v122, v123
	v_add_f32_e32 v124, v124, v125
	v_add_f32_e32 v126, v126, v127
	v_add_f32_e32 v128, v128, v129
	v_add_f32_e32 v130, v130, v131
	v_add_f32_e32 v132, v132, v133
	v_add_f32_e32 v134, v134, v135
	v_add_f32_e32 v120, v120, v122
	v_add_f32_e32 v124, v124, v126
	v_add_f32_e32 v128, v128, v130
	v_add_f32_e32 v132, v132, v134
	v_add_f32_e32 v120, v120, v124
	v_add_f32_e32 v128, v128, v132
	v_add_f32_e32 v120, v120, v128
	v_cvt_pk_bf16_f32 v140, v120, v149
	global_store_short v[138:139], v140, off
	s_cmpk_eq_i32 s25, 0x7f
	s_cbranch_scc1 .Lsc_h2s
	v_add_u32_e32 v8, 16, v68
	v_ashrrev_i32_e32 v9, 31, v8
	v_lshl_add_u64 v[8:9], s[38:39], 0, v[8:9]
	v_mad_u64_u32 v[10:11], s[10:11], v8, s75, v[60:61]
	v_mad_u64_u32 v[34:35], s[10:11], v8, s89, v[62:63]
	v_cmp_lt_i32_e32 vcc, -16, v68
	v_mad_i32_i24 v11, v9, s75, v11
	v_mad_i32_i24 v35, v9, s89, v35
	v_cndmask_b32_e64 v39, 0, -1, vcc
	v_cndmask_b32_e32 v38, 0, v178, vcc
	global_load_dwordx2 v[28:29], v[10:11], off offset:3072
	global_load_dwordx2 v[30:31], v[10:11], off
	global_load_dwordx2 v[32:33], v[10:11], off offset:1536
	global_load_dwordx2 v[36:37], v[34:35], off
	v_lshl_add_u64 v[8:9], v[10:11], 0, v[38:39]
	global_load_dwordx2 v[68:69], v[8:9], off offset:3072
	global_load_dwordx2 v[72:73], v[8:9], off offset:1536
	global_load_dwordx2 v[74:75], v[8:9], off
	ds_read_b128 v[12:15], v84
	ds_read_b128 v[16:19], v85
	ds_read_b128 v[20:23], v86
	ds_read_b128 v[24:27], v87
	ds_read_b128 v[8:11], v88
	global_load_dwordx2 v[34:35], v[34:35], off offset:1536
	v_add_u32_e32 v70, s44, v93
.Lsc_h2s:
	s_waitcnt lgkmcnt(0)
	s_barrier
	ds_read_b128 v[120:123], v145 offset:0
	ds_read_b128 v[124:127], v145 offset:16
	ds_read_b128 v[128:131], v145 offset:32
	ds_read_b128 v[132:135], v145 offset:48
	s_add_i32 s10, s26, 8
	s_ashr_i32 s11, s10, 31
	v_lshl_add_u64 v[136:137], v[64:65], 0, s[10:11]
	v_mad_u64_u32 v[138:139], s[12:13], v136, s74, v[66:67]
	v_mad_i32_i24 v139, v137, s74, v139
	s_waitcnt lgkmcnt(0)
	v_add_f32_e32 v120, v120, v121
	v_add_f32_e32 v122, v122, v123
	v_add_f32_e32 v124, v124, v125
	v_add_f32_e32 v126, v126, v127
	v_add_f32_e32 v128, v128, v129
	v_add_f32_e32 v130, v130, v131
	v_add_f32_e32 v132, v132, v133
	v_add_f32_e32 v134, v134, v135
	v_add_f32_e32 v120, v120, v122
	v_add_f32_e32 v124, v124, v126
	v_add_f32_e32 v128, v128, v130
	v_add_f32_e32 v132, v132, v134
	v_add_f32_e32 v120, v120, v124
	v_add_f32_e32 v128, v128, v132
	v_add_f32_e32 v120, v120, v128
	v_cvt_pk_bf16_f32 v140, v120, v149
	global_store_short v[138:139], v140, off
	s_cmpk_eq_i32 s25, 0x7f
	s_cbranch_scc1 .Lsc_h3s
	s_waitcnt vmcnt(7)
	v_lshlrev_b32_e32 v76, 16, v28
	s_waitcnt vmcnt(6)
	v_lshlrev_b32_e32 v80, 16, v30
	v_and_b32_e32 v81, 0xffff0000, v30
	v_lshlrev_b32_e32 v82, 16, v31
	v_and_b32_e32 v83, 0xffff0000, v31
	s_waitcnt vmcnt(4)
	v_lshlrev_b32_e32 v30, 16, v37
	v_and_b32_e32 v31, 0xffff0000, v37
	s_waitcnt vmcnt(3)
	v_and_b32_e32 v37, v68, v39
	s_waitcnt vmcnt(2)
	v_and_b32_e32 v102, v72, v39
	v_and_b32_e32 v77, 0xffff0000, v28
	v_lshlrev_b32_e32 v78, 16, v29
	v_and_b32_e32 v79, 0xffff0000, v29
	v_lshlrev_b32_e32 v100, 16, v32
	v_and_b32_e32 v101, 0xffff0000, v32
	v_lshlrev_b32_e32 v28, 16, v36
	v_and_b32_e32 v29, 0xffff0000, v36
	v_and_b32_e32 v103, v73, v39
	s_waitcnt vmcnt(1)
	v_and_b32_e32 v73, v75, v39
	v_and_b32_e32 v72, v74, v39
	v_lshlrev_b32_e32 v36, 16, v37
	v_and_b32_e32 v37, 0xffff0000, v37
	v_lshlrev_b32_e32 v74, 16, v102
	v_and_b32_e32 v75, 0xffff0000, v102
	v_lshlrev_b32_e32 v32, 16, v33
	v_and_b32_e32 v33, 0xffff0000, v33
	v_lshlrev_b32_e32 v102, 16, v103
	v_and_b32_e32 v103, 0xffff0000, v103
	v_pk_add_f32 v[36:37], v[36:37], v[76:77] neg_lo:[0,1] neg_hi:[0,1]
	v_pk_add_f32 v[74:75], v[74:75], v[100:101] neg_lo:[0,1] neg_hi:[0,1]
	v_pk_add_f32 v[102:103], v[102:103], v[32:33] neg_lo:[0,1] neg_hi:[0,1]
	s_waitcnt lgkmcnt(2)
	v_pk_fma_f32 v[20:21], v[36:37], v[20:21], v[76:77]
	v_pk_fma_f32 v[36:37], v[74:75], v[16:17], v[100:101]
	v_pk_fma_f32 v[32:33], v[102:103], v[18:19], v[32:33]
	s_waitcnt lgkmcnt(1)
	v_pk_mul_f32 v[24:25], v[24:25], v[36:37]
	v_pk_mul_f32 v[26:27], v[26:27], v[32:33]
	v_pk_mul_f32 v[16:17], v[24:25], v[24:25]
	v_pk_mul_f32 v[18:19], v[26:27], v[26:27]
	v_add_f32_e32 v16, v16, v17
	v_add_f32_e32 v16, v18, v16
	v_add_f32_e32 v16, v19, v16
	v_and_b32_e32 v69, v69, v39
	v_lshlrev_b32_e32 v38, 16, v69
	v_add_f32_dpp v16, v16, v16 row_ror:8 row_mask:0xf bank_mask:0xf bound_ctrl:1
	v_and_b32_e32 v39, 0xffff0000, v69
	v_pk_add_f32 v[38:39], v[38:39], v[78:79] neg_lo:[0,1] neg_hi:[0,1]
	v_add_f32_dpp v16, v16, v16 row_ror:4 row_mask:0xf bank_mask:0xf bound_ctrl:1
	v_pk_fma_f32 v[22:23], v[38:39], v[22:23], v[78:79]
	v_mul_f32_e32 v28, 0x3fb8aa3b, v28
	v_add_f32_dpp v16, v16, v16 row_ror:2 row_mask:0xf bank_mask:0xf bound_ctrl:1
	v_mul_f32_e32 v29, 0x3fb8aa3b, v29
	v_mul_f32_e32 v30, 0x3fb8aa3b, v30
	v_add_f32_dpp v16, v16, v16 row_ror:1 row_mask:0xf bank_mask:0xf bound_ctrl:1
	v_mul_f32_e32 v17, 0x4f800000, v16
	v_cmp_gt_f32_e32 vcc, s95, v16
	v_mul_f32_e32 v31, 0x3fb8aa3b, v31
	v_exp_f32_e32 v28, v28
	v_cndmask_b32_e32 v16, v16, v17, vcc
	v_sqrt_f32_e32 v17, v16
	v_exp_f32_e32 v29, v29
	v_exp_f32_e32 v30, v30
	v_exp_f32_e32 v31, v31
	v_add_u32_e32 v18, -1, v17
	v_add_u32_e32 v19, 1, v17
	v_fma_f32 v38, -v18, v17, v16
	v_fma_f32 v39, -v19, v17, v16
	v_cmp_ge_f32_e64 s[10:11], 0, v38
	ds_write_b128 v70, v[28:31] offset:24576
	v_lshlrev_b32_e32 v68, 16, v72
	v_cndmask_b32_e64 v17, v17, v18, s[10:11]
	v_cmp_lt_f32_e64 s[10:11], 0, v39
	v_and_b32_e32 v69, 0xffff0000, v72
	v_lshlrev_b32_e32 v72, 16, v73
	v_cndmask_b32_e64 v17, v17, v19, s[10:11]
	v_mul_f32_e32 v18, 0x37800000, v17
	v_cndmask_b32_e32 v17, v17, v18, vcc
	v_cmp_class_f32_e32 vcc, v16, v170
	v_and_b32_e32 v73, 0xffff0000, v73
	v_pk_add_f32 v[68:69], v[68:69], v[80:81] neg_lo:[0,1] neg_hi:[0,1]
	v_cndmask_b32_e32 v16, v17, v16, vcc
	v_max_f32_e32 v16, 0x2b8cbccc, v16
	v_div_scale_f32 v17, s[10:11], v16, v16, 1.0
	v_rcp_f32_e32 v18, v17
	v_div_scale_f32 v19, vcc, 1.0, v16, 1.0
	v_pk_add_f32 v[72:73], v[72:73], v[82:83] neg_lo:[0,1] neg_hi:[0,1]
	v_fma_f32 v28, -v17, v18, 1.0
	v_fmac_f32_e32 v18, v28, v18
	v_mul_f32_e32 v28, v19, v18
	v_fma_f32 v29, -v17, v28, v19
	v_fmac_f32_e32 v28, v29, v18
	v_fma_f32 v17, -v17, v28, v19
	v_div_fmas_f32 v17, v17, v18, v28
	v_div_fixup_f32 v28, v17, v16, 1.0
	v_pk_mul_f32 v[18:19], v[26:27], v[28:29] op_sel_hi:[1,0] neg_lo:[0,1] neg_hi:[0,1]
	v_pk_mul_f32 v[16:17], v[24:25], v[28:29] op_sel_hi:[1,0] neg_lo:[0,1] neg_hi:[0,1]
	v_pk_mul_f32 v[24:25], v[24:25], v[28:29] op_sel_hi:[1,0]
	ds_write_b128 v70, v[16:19] offset:24832
	v_pk_mul_f32 v[16:17], v[26:27], v[28:29] op_sel_hi:[1,0]
	s_waitcnt vmcnt(0)
	v_lshlrev_b32_e32 v26, 16, v34
	v_and_b32_e32 v27, 0xffff0000, v34
	v_lshlrev_b32_e32 v28, 16, v35
	v_and_b32_e32 v29, 0xffff0000, v35
	v_pk_mul_f32 v[18:19], v[16:17], v[28:29]
	v_pk_mul_f32 v[16:17], v[24:25], v[26:27]
	ds_write_b128 v70, v[16:19] offset:25088
	v_pk_add_f32 v[16:17], v[28:29], -1.0 op_sel_hi:[1,0]
	v_pk_add_f32 v[18:19], v[26:27], -1.0 op_sel_hi:[1,0]
	s_waitcnt lgkmcnt(3)
	v_pk_fma_f32 v[10:11], v[16:17], v[10:11], 1.0 op_sel_hi:[1,1,0]
	v_pk_fma_f32 v[8:9], v[18:19], v[8:9], 1.0 op_sel_hi:[1,1,0]
	v_pk_mul_f32 v[10:11], v[32:33], v[10:11]
	v_pk_mul_f32 v[8:9], v[36:37], v[8:9]
	v_pk_fma_f32 v[12:13], v[68:69], v[12:13], v[80:81]
	v_pk_fma_f32 v[14:15], v[72:73], v[14:15], v[82:83]
	ds_write_b128 v70, v[8:11] offset:25344
	ds_write_b128 v70, v[12:15] offset:25600
	ds_write_b128 v70, v[20:23] offset:25856
.Lsc_h3s:
	s_waitcnt lgkmcnt(0)
	s_barrier
.Lsc_next:
	s_add_i32 s25, s25, 1
	s_cmpk_lg_i32 s25, 0x80
	s_cbranch_scc1 .LBB0_141
	s_cmp_lg_u64 s[8:9], 0
	s_cbranch_scc0 .LBB0_132
	s_lshl_b32 s26, s25, 5
	ds_read_b128 v[120:123], v145 offset:16384
	ds_read_b128 v[124:127], v145 offset:16400
	ds_read_b128 v[128:131], v145 offset:16416
	ds_read_b128 v[132:135], v145 offset:16432
	s_add_i32 s10, s26, -16
	s_ashr_i32 s11, s10, 31
	v_lshl_add_u64 v[136:137], v[64:65], 0, s[10:11]
	v_mad_u64_u32 v[138:139], s[12:13], v136, s74, v[66:67]
	v_mad_i32_i24 v139, v137, s74, v139
	s_waitcnt lgkmcnt(0)
	v_add_f32_e32 v120, v120, v121
	v_add_f32_e32 v122, v122, v123
	v_add_f32_e32 v124, v124, v125
	v_add_f32_e32 v126, v126, v127
	v_add_f32_e32 v128, v128, v129
	v_add_f32_e32 v130, v130, v131
	v_add_f32_e32 v132, v132, v133
	v_add_f32_e32 v134, v134, v135
	v_add_f32_e32 v120, v120, v122
	v_add_f32_e32 v124, v124, v126
	v_add_f32_e32 v128, v128, v130
	v_add_f32_e32 v132, v132, v134
	v_add_f32_e32 v120, v120, v124
	v_add_f32_e32 v128, v128, v132
	v_add_f32_e32 v120, v120, v128
	v_cvt_pk_bf16_f32 v140, v120, v149
	global_store_short v[138:139], v140, off
	s_branch .LBB0_132
